# GEMM K-loops: back edge rotated out of the phase-1 head (loop-back barrier is the loop head; next-iteration address SALU block + exit test moved in front of it; exit path has its own barrier copy)
# baseline (speedup 1.0000x reference)
; #define PG8_STAGE(bufoff, gbase, voff) do { _Pragma("unroll") for (int _i = 0; _i < 2; ++_i) \
;         __builtin_amdgcn_global_load_lds((const unsigned*)((const char*)(gbase) + (voff)[_i]), (LAS unsigned*)(lds + (bufoff) + ldsw + _i * 8192), 16, 0, 0); } while (0)
; #define PG8_LDA(dst, b, h) do { _Pragma("unroll") for (int m = 0; m < 4; ++m) _Pragma("unroll") for (int k = 0; k < 2; ++k) dst[m][k] = *(const LAS bf16x8*)(lds + PG8_SA(b, h) + aoff + m * 2048 + k * 1024); } while (0)
; #define PG8_LDB(dst, b, h) do { _Pragma("unroll") for (int n = 0; n < 2; ++n) _Pragma("unroll") for (int k = 0; k < 2; ++k) dst[n][k] = *(const LAS bf16x8*)(lds + PG8_SB(b, h) + boff + n * 2048 + k * 1024); } while (0)
; #define PG8_SCHED __builtin_amdgcn_sched_barrier(0)
; template <class Epi, class Sched, int LD>
; __device__ __forceinline__ void gemm_phase(LAS unsigned char* lds, const Gemm g, const Sched& S, const Epi& E) {
;     ...
;         const bool has_next = S.next(ui + 1, nxt);
;         const char* nA = has_next ? (const char*)g.A + (size_t)nxt.pm * tstep + (size_t)(nxt.kofs / BK) * kstep : cA; const char* nB = has_next ? (const char*)g.Bt + (size_t)nxt.pn * tstep + (size_t)(nxt.kofs / BK) * kstep : cB;
;         const int nt = cur.nt;
;         for (int t = 0; t < nt; t += 2) {
;             const bool last = (t == nt - 2);
;             const char* a1 = cA + (size_t)(t + 1) * kstep;
;             const char* a2 = last ? nA : cA + (size_t)(t + 2) * kstep; const char* b2 = last ? nB : cB + (size_t)(t + 2) * kstep;
;             const char* a3 = a2 + kstep; const char* b3 = b2 + kstep;
;             PG8_LDB(B0, 0, 0); PG8_SCHED; PG8_LDA(At, 0, 0); PG8_STAGE(PG8_SA(1, 1), a1 + hstep, voffA);
;     ...
;         for (int a = 0; a < 2; ++a)
; #pragma unroll
;             for (int b = 0; b < 2; ++b)
; #pragma unroll
;                 for (int m = 0; m < 4; ++m)
; #pragma unroll
;                     for (int n = 0; n < 2; ++n) acc[a][b][m][n] = (f32x4){0.f, 0.f, 0.f, 0.f};
;         cur = nxt; cA = nA; cB = nB; ++ui;
.LBB0_57:
	s_add_i32 s68, s65, -2
	s_add_u32 s46, s46, 0xc000
	s_addc_u32 s47, s47, 0
	s_add_u32 s69, s48, 0x10000
	v_mov_b32_e32 v4, 0
	s_addc_u32 s70, s49, 0
	s_mov_b32 s4, 0
	v_mov_b32_e32 v5, v4
	v_mov_b32_e32 v6, v4
	v_mov_b32_e32 v7, v4
	s_waitcnt vmcnt(0)
	v_mov_b32_e32 v8, v4
	v_mov_b32_e32 v9, v4
	v_mov_b32_e32 v10, v4
	v_mov_b32_e32 v11, v4
	v_mov_b32_e32 v20, v4
	v_mov_b32_e32 v21, v4
	v_mov_b32_e32 v22, v4
	v_mov_b32_e32 v23, v4
	v_mov_b32_e32 v24, v4
	v_mov_b32_e32 v25, v4
	v_mov_b32_e32 v26, v4
	v_mov_b32_e32 v27, v4
	v_mov_b32_e32 v36, v4
	v_mov_b32_e32 v37, v4
	v_mov_b32_e32 v38, v4
	v_mov_b32_e32 v39, v4
	v_mov_b32_e32 v40, v4
	v_mov_b32_e32 v41, v4
	v_mov_b32_e32 v42, v4
	v_mov_b32_e32 v43, v4
	v_mov_b32_e32 v52, v4
	v_mov_b32_e32 v53, v4
	v_mov_b32_e32 v54, v4
	v_mov_b32_e32 v55, v4
	v_mov_b32_e32 v56, v4
	v_mov_b32_e32 v57, v4
	v_mov_b32_e32 v58, v4
	v_mov_b32_e32 v59, v4
	v_mov_b32_e32 v12, v4
	v_mov_b32_e32 v13, v4
	v_mov_b32_e32 v14, v4
	v_mov_b32_e32 v15, v4
	v_mov_b32_e32 v16, v4
	v_mov_b32_e32 v17, v4
	v_mov_b32_e32 v18, v4
	v_mov_b32_e32 v19, v4
	v_mov_b32_e32 v28, v4
	v_mov_b32_e32 v29, v4
	v_mov_b32_e32 v30, v4
	v_mov_b32_e32 v31, v4
	v_mov_b32_e32 v32, v4
	v_mov_b32_e32 v33, v4
	v_mov_b32_e32 v34, v4
	v_mov_b32_e32 v35, v4
	v_mov_b32_e32 v44, v4
	v_mov_b32_e32 v45, v4
	v_mov_b32_e32 v46, v4
	v_mov_b32_e32 v47, v4
	v_mov_b32_e32 v48, v4
	v_mov_b32_e32 v49, v4
	v_mov_b32_e32 v50, v4
	v_mov_b32_e32 v51, v4
	v_mov_b32_e32 v60, v4
	v_mov_b32_e32 v61, v4
	v_mov_b32_e32 v62, v4
	v_mov_b32_e32 v63, v4
	v_mov_b32_e32 v64, v4
	v_mov_b32_e32 v65, v4
	v_mov_b32_e32 v66, v4
	v_mov_b32_e32 v67, v4
	v_mov_b32_e32 v68, v4
	v_mov_b32_e32 v69, v4
	v_mov_b32_e32 v70, v4
	v_mov_b32_e32 v71, v4
	v_mov_b32_e32 v72, v4
	v_mov_b32_e32 v73, v4
	v_mov_b32_e32 v74, v4
	v_mov_b32_e32 v75, v4
	v_mov_b32_e32 v84, v4
	v_mov_b32_e32 v85, v4
	v_mov_b32_e32 v86, v4
	v_mov_b32_e32 v87, v4
	v_mov_b32_e32 v88, v4
	v_mov_b32_e32 v89, v4
	v_mov_b32_e32 v90, v4
	v_mov_b32_e32 v91, v4
	v_mov_b32_e32 v100, v4
	v_mov_b32_e32 v101, v4
	v_mov_b32_e32 v102, v4
	v_mov_b32_e32 v103, v4
	v_mov_b32_e32 v104, v4
	v_mov_b32_e32 v105, v4
	v_mov_b32_e32 v106, v4
	v_mov_b32_e32 v107, v4
	v_mov_b32_e32 v116, v4
	v_mov_b32_e32 v117, v4
	v_mov_b32_e32 v118, v4
	v_mov_b32_e32 v119, v4
	v_mov_b32_e32 v120, v4
	v_mov_b32_e32 v121, v4
	v_mov_b32_e32 v122, v4
	v_mov_b32_e32 v123, v4
	v_mov_b32_e32 v76, v4
	v_mov_b32_e32 v77, v4
	v_mov_b32_e32 v78, v4
	v_mov_b32_e32 v79, v4
	v_mov_b32_e32 v80, v4
	v_mov_b32_e32 v81, v4
	v_mov_b32_e32 v82, v4
	v_mov_b32_e32 v83, v4
	v_mov_b32_e32 v92, v4
	v_mov_b32_e32 v93, v4
	v_mov_b32_e32 v94, v4
	v_mov_b32_e32 v95, v4
	v_mov_b32_e32 v96, v4
	v_mov_b32_e32 v97, v4
	v_mov_b32_e32 v98, v4
	v_mov_b32_e32 v99, v4
	v_mov_b32_e32 v108, v4
	v_mov_b32_e32 v109, v4
	v_mov_b32_e32 v110, v4
	v_mov_b32_e32 v111, v4
	v_mov_b32_e32 v112, v4
	v_mov_b32_e32 v113, v4
	v_mov_b32_e32 v114, v4
	v_mov_b32_e32 v115, v4
	v_mov_b32_e32 v124, v4
	v_mov_b32_e32 v125, v4
	v_mov_b32_e32 v126, v4
	v_mov_b32_e32 v127, v4
	v_mov_b32_e32 v128, v4
	v_mov_b32_e32 v129, v4
	v_mov_b32_e32 v130, v4
	v_mov_b32_e32 v131, v4
	ds_read_b128 v[140:143], v228
	ds_read_b128 v[150:153], v228 offset:1024
	ds_read_b128 v[154:157], v228 offset:2048
	ds_read_b128 v[176:179], v228 offset:3072
	s_add_i32 s71, s4, 2
	s_add_u32 s48, s46, 0x4000
	s_addc_u32 s5, s47, 0
	s_cmp_eq_u32 s68, s4
	s_cselect_b32 s4, s42, s48
	s_cselect_b32 s5, s43, s5
	s_cselect_b32 s48, s44, s69
	s_cselect_b32 s49, s45, s70
	s_add_u32 s50, s4, 0x8000
	s_addc_u32 s51, s5, 0
	s_add_i32 s72, 0, 0x10000
	s_branch .Lrot_out_body

; #define PG8_STAGE(bufoff, gbase, voff) do { _Pragma("unroll") for (int _i = 0; _i < 2; ++_i) \
;         __builtin_amdgcn_global_load_lds((const unsigned*)((const char*)(gbase) + (voff)[_i]), (LAS unsigned*)(lds + (bufoff) + ldsw + _i * 8192), 16, 0, 0); } while (0)
; #define PG8_LDA(dst, b, h) do { _Pragma("unroll") for (int m = 0; m < 4; ++m) _Pragma("unroll") for (int k = 0; k < 2; ++k) dst[m][k] = *(const LAS bf16x8*)(lds + PG8_SA(b, h) + aoff + m * 2048 + k * 1024); } while (0)
; #define PG8_LDB(dst, b, h) do { _Pragma("unroll") for (int n = 0; n < 2; ++n) _Pragma("unroll") for (int k = 0; k < 2; ++k) dst[n][k] = *(const LAS bf16x8*)(lds + PG8_SB(b, h) + boff + n * 2048 + k * 1024); } while (0)
; #define PG8_MMA(ai, bj, At, Bt) do { __builtin_amdgcn_s_setprio(1); _Pragma("unroll") for (int m = 0; m < 4; ++m) _Pragma("unroll") for (int n = 0; n < 2; ++n) _Pragma("unroll") for (int k = 0; k < 2; ++k) \
;         acc[ai][bj][m][n] = __builtin_amdgcn_mfma_f32_16x16x32_bf16(Bt[n][k], At[m][k], acc[ai][bj][m][n], 0, 0, 0); __builtin_amdgcn_s_setprio(0); } while (0)
; #define PG8_WAIT_V(n) asm volatile("s_waitcnt vmcnt(" #n ")" ::: "memory")
; #define PG8_WAIT_L(n) asm volatile("s_waitcnt lgkmcnt(" #n ")" ::: "memory")
; #define PG8_BAR __builtin_amdgcn_s_barrier()
; #define PG8_SCHED __builtin_amdgcn_sched_barrier(0)
; template <class Epi, class Sched, int LD>
; __device__ __forceinline__ void gemm_phase(LAS unsigned char* lds, const Gemm g, const Sched& S, const Epi& E) {
;     ...
;             PG8_LDB(B0, 0, 0); PG8_SCHED; PG8_LDA(At, 0, 0); PG8_STAGE(PG8_SA(1, 1), a1 + hstep, voffA);
;             PG8_WAIT_L(8); PG8_BAR; PG8_WAIT_L(0); PG8_MMA(0, 0, At, B0); PG8_BAR; PG8_SCHED;
;             PG8_LDB(B1, 0, 1); PG8_STAGE(PG8_SB(0, 0), b2, voffB);
;             PG8_BAR; PG8_WAIT_L(0); PG8_MMA(0, 1, At, B1); PG8_BAR;
;             PG8_LDA(At, 0, 1); PG8_STAGE(PG8_SA(0, 0), a2, voffA);
;             PG8_BAR; PG8_WAIT_L(0); PG8_MMA(1, 0, At, B0); PG8_BAR; PG8_SCHED;
;             PG8_STAGE(PG8_SB(0, 1), b2 + hstep, voffB);
;             PG8_WAIT_V(6); PG8_BAR; PG8_MMA(1, 1, At, B1); PG8_BAR;
;             PG8_LDB(B0, 1, 0); PG8_SCHED; PG8_LDA(At, 1, 0); PG8_STAGE(PG8_SA(0, 1), a2 + hstep, voffA);
.Lrot_out_body:
	s_add_i32 m0, s39, 0xc000
	ds_read_b128 v[180:183], v148
	ds_read_b128 v[184:187], v148 offset:1024
	ds_read_b128 v[188:191], v148 offset:2048
	ds_read_b128 v[192:195], v148 offset:3072
	ds_read_b128 v[196:199], v148 offset:4096
	ds_read_b128 v[200:203], v148 offset:5120
	ds_read_b128 v[204:207], v148 offset:6144
	ds_read_b128 v[208:211], v148 offset:7168
	global_load_lds_dwordx4 v132, s[46:47]
	s_add_i32 m0, s39, 0xe000
	s_nop 0
	global_load_lds_dwordx4 v138, s[46:47]
	s_waitcnt lgkmcnt(8)
	s_barrier
	s_waitcnt lgkmcnt(0)
	s_setprio 0
	v_mfma_f32_16x16x32_bf16 v[128:131], v[140:143], v[180:183], v[128:131]
	v_mfma_f32_16x16x32_bf16 v[124:127], v[154:157], v[180:183], v[124:127]
	v_mfma_f32_16x16x32_bf16 v[112:115], v[140:143], v[188:191], v[112:115]
	v_mfma_f32_16x16x32_bf16 v[108:111], v[154:157], v[188:191], v[108:111]
	v_mfma_f32_16x16x32_bf16 v[96:99], v[140:143], v[196:199], v[96:99]
	v_mfma_f32_16x16x32_bf16 v[92:95], v[154:157], v[196:199], v[92:95]
	v_mfma_f32_16x16x32_bf16 v[80:83], v[140:143], v[204:207], v[80:83]
	v_mfma_f32_16x16x32_bf16 v[76:79], v[154:157], v[204:207], v[76:79]
	v_mfma_f32_16x16x32_bf16 v[128:131], v[150:153], v[184:187], v[128:131]
	v_mfma_f32_16x16x32_bf16 v[124:127], v[176:179], v[184:187], v[124:127]
	v_mfma_f32_16x16x32_bf16 v[112:115], v[150:153], v[192:195], v[112:115]
	v_mfma_f32_16x16x32_bf16 v[108:111], v[176:179], v[192:195], v[108:111]
	v_mfma_f32_16x16x32_bf16 v[96:99], v[150:153], v[200:203], v[96:99]
	v_mfma_f32_16x16x32_bf16 v[92:95], v[176:179], v[200:203], v[92:95]
	s_setprio 3
	s_barrier
	v_mfma_f32_16x16x32_bf16 v[80:83], v[150:153], v[208:211], v[80:83]
	v_mfma_f32_16x16x32_bf16 v[76:79], v[176:179], v[208:211], v[76:79]
	s_setprio 2
	s_add_i32 s74, 0, 0x14000
	s_add_i32 s72, s72, s29
	ds_read_b128 v[212:215], v228 offset:16384
	ds_read_b128 v[216:219], v228 offset:17408
	ds_read_b128 v[220:223], v228 offset:18432
	ds_read_b128 v[224:227], v228 offset:19456
	s_mov_b32 m0, s72
	s_nop 0
	global_load_lds_dwordx4 v132, s[48:49]
	s_add_i32 m0, s72, 0x2000
	s_nop 0
	global_load_lds_dwordx4 v138, s[48:49]
	s_barrier
	s_waitcnt lgkmcnt(0)
	s_setprio 0
	v_mfma_f32_16x16x32_bf16 v[120:123], v[212:215], v[180:183], v[120:123]
	v_mfma_f32_16x16x32_bf16 v[116:119], v[220:223], v[180:183], v[116:119]
	v_mfma_f32_16x16x32_bf16 v[104:107], v[212:215], v[188:191], v[104:107]
	v_mfma_f32_16x16x32_bf16 v[100:103], v[220:223], v[188:191], v[100:103]
	v_mfma_f32_16x16x32_bf16 v[88:91], v[212:215], v[196:199], v[88:91]
	v_mfma_f32_16x16x32_bf16 v[84:87], v[220:223], v[196:199], v[84:87]
	v_mfma_f32_16x16x32_bf16 v[72:75], v[212:215], v[204:207], v[72:75]
	v_mfma_f32_16x16x32_bf16 v[68:71], v[220:223], v[204:207], v[68:71]
	v_mfma_f32_16x16x32_bf16 v[120:123], v[216:219], v[184:187], v[120:123]
	v_mfma_f32_16x16x32_bf16 v[116:119], v[224:227], v[184:187], v[116:119]
	v_mfma_f32_16x16x32_bf16 v[104:107], v[216:219], v[192:195], v[104:107]
	v_mfma_f32_16x16x32_bf16 v[100:103], v[224:227], v[192:195], v[100:103]
	v_mfma_f32_16x16x32_bf16 v[88:91], v[216:219], v[200:203], v[88:91]
	v_mfma_f32_16x16x32_bf16 v[84:87], v[224:227], v[200:203], v[84:87]
	v_mfma_f32_16x16x32_bf16 v[72:75], v[216:219], v[208:211], v[72:75]
	v_mfma_f32_16x16x32_bf16 v[68:71], v[224:227], v[208:211], v[68:71]
	s_setprio 2
	s_mov_b32 m0, s39
	s_barrier
	ds_read_b128 v[180:183], v148 offset:16384
	ds_read_b128 v[184:187], v148 offset:17408
	ds_read_b128 v[188:191], v148 offset:18432
	ds_read_b128 v[192:195], v148 offset:19456
	ds_read_b128 v[196:199], v148 offset:20480
	ds_read_b128 v[200:203], v148 offset:21504
	ds_read_b128 v[204:207], v148 offset:22528
	ds_read_b128 v[208:211], v148 offset:23552
	global_load_lds_dwordx4 v132, s[4:5]
	s_mov_b32 m0, s52
	s_nop 0
	global_load_lds_dwordx4 v138, s[4:5]
	s_waitcnt vmcnt(10)
	s_barrier
	s_waitcnt lgkmcnt(0)
	s_setprio 0
	v_mfma_f32_16x16x32_bf16 v[64:67], v[140:143], v[180:183], v[64:67]
	v_mfma_f32_16x16x32_bf16 v[60:63], v[154:157], v[180:183], v[60:63]
	v_mfma_f32_16x16x32_bf16 v[48:51], v[140:143], v[188:191], v[48:51]
	v_mfma_f32_16x16x32_bf16 v[44:47], v[154:157], v[188:191], v[44:47]
	v_mfma_f32_16x16x32_bf16 v[32:35], v[140:143], v[196:199], v[32:35]
	v_mfma_f32_16x16x32_bf16 v[28:31], v[154:157], v[196:199], v[28:31]
	v_mfma_f32_16x16x32_bf16 v[16:19], v[140:143], v[204:207], v[16:19]
	v_mfma_f32_16x16x32_bf16 v[12:15], v[154:157], v[204:207], v[12:15]
	v_mfma_f32_16x16x32_bf16 v[64:67], v[150:153], v[184:187], v[64:67]
	v_mfma_f32_16x16x32_bf16 v[60:63], v[176:179], v[184:187], v[60:63]
	v_mfma_f32_16x16x32_bf16 v[48:51], v[150:153], v[192:195], v[48:51]
	v_mfma_f32_16x16x32_bf16 v[44:47], v[176:179], v[192:195], v[44:47]
	v_mfma_f32_16x16x32_bf16 v[32:35], v[150:153], v[200:203], v[32:35]
	v_mfma_f32_16x16x32_bf16 v[28:31], v[176:179], v[200:203], v[28:31]
	s_setprio 3
	s_barrier
	v_mfma_f32_16x16x32_bf16 v[16:19], v[150:153], v[208:211], v[16:19]
	v_mfma_f32_16x16x32_bf16 v[12:15], v[176:179], v[208:211], v[12:15]
	s_setprio 2
	ds_read_b128 v[140:143], v228 offset:32768
	ds_read_b128 v[150:153], v228 offset:33792
	ds_read_b128 v[154:157], v228 offset:34816
	ds_read_b128 v[176:179], v228 offset:35840
	s_add_u32 s72, s48, 0x4000
	s_addc_u32 s73, s49, 0
	s_add_i32 s74, s74, s29
	s_mov_b32 m0, s74
	s_nop 0
	global_load_lds_dwordx4 v132, s[72:73]
	s_add_i32 m0, s74, 0x2000
	s_nop 0
	global_load_lds_dwordx4 v138, s[72:73]
	s_waitcnt vmcnt(6)
	s_barrier
; #define PG8_STAGE(bufoff, gbase, voff) do { _Pragma("unroll") for (int _i = 0; _i < 2; ++_i) \
;         __builtin_amdgcn_global_load_lds((const unsigned*)((const char*)(gbase) + (voff)[_i]), (LAS unsigned*)(lds + (bufoff) + ldsw + _i * 8192), 16, 0, 0); } while (0)
; #define PG8_LDA(dst, b, h) do { _Pragma("unroll") for (int m = 0; m < 4; ++m) _Pragma("unroll") for (int k = 0; k < 2; ++k) dst[m][k] = *(const LAS bf16x8*)(lds + PG8_SA(b, h) + aoff + m * 2048 + k * 1024); } while (0)
; #define PG8_LDB(dst, b, h) do { _Pragma("unroll") for (int n = 0; n < 2; ++n) _Pragma("unroll") for (int k = 0; k < 2; ++k) dst[n][k] = *(const LAS bf16x8*)(lds + PG8_SB(b, h) + boff + n * 2048 + k * 1024); } while (0)
; #define PG8_MMA(ai, bj, At, Bt) do { __builtin_amdgcn_s_setprio(1); _Pragma("unroll") for (int m = 0; m < 4; ++m) _Pragma("unroll") for (int n = 0; n < 2; ++n) _Pragma("unroll") for (int k = 0; k < 2; ++k) \
;         acc[ai][bj][m][n] = __builtin_amdgcn_mfma_f32_16x16x32_bf16(Bt[n][k], At[m][k], acc[ai][bj][m][n], 0, 0, 0); __builtin_amdgcn_s_setprio(0); } while (0)
; #define PG8_WAIT_V(n) asm volatile("s_waitcnt vmcnt(" #n ")" ::: "memory")
; #define PG8_WAIT_L(n) asm volatile("s_waitcnt lgkmcnt(" #n ")" ::: "memory")
; #define PG8_BAR __builtin_amdgcn_s_barrier()
; #define PG8_SCHED __builtin_amdgcn_sched_barrier(0)
; template <class Epi, class Sched, int LD>
; __device__ __forceinline__ void gemm_phase(LAS unsigned char* lds, const Gemm g, const Sched& S, const Epi& E) {
;     ...
;             PG8_WAIT_V(6); PG8_BAR; PG8_MMA(1, 1, At, B1); PG8_BAR;
;             PG8_LDB(B0, 1, 0); PG8_SCHED; PG8_LDA(At, 1, 0); PG8_STAGE(PG8_SA(0, 1), a2 + hstep, voffA);
;             PG8_WAIT_L(8); PG8_BAR; PG8_WAIT_L(0); PG8_MMA(0, 0, At, B0); PG8_BAR; PG8_SCHED;
;             PG8_LDB(B1, 1, 1); PG8_STAGE(PG8_SB(1, 0), b3, voffB);
;             PG8_BAR; PG8_WAIT_L(0); PG8_MMA(0, 1, At, B1); PG8_BAR;
;             PG8_LDA(At, 1, 1); PG8_STAGE(PG8_SA(1, 0), a3, voffA);
;             PG8_BAR; PG8_WAIT_L(0); PG8_MMA(1, 0, At, B0); PG8_BAR; PG8_SCHED;
	s_setprio 0
	v_mfma_f32_16x16x32_bf16 v[56:59], v[212:215], v[180:183], v[56:59]
	v_mfma_f32_16x16x32_bf16 v[52:55], v[220:223], v[180:183], v[52:55]
	v_mfma_f32_16x16x32_bf16 v[40:43], v[212:215], v[188:191], v[40:43]
	v_mfma_f32_16x16x32_bf16 v[36:39], v[220:223], v[188:191], v[36:39]
	v_mfma_f32_16x16x32_bf16 v[24:27], v[212:215], v[196:199], v[24:27]
	v_mfma_f32_16x16x32_bf16 v[20:23], v[220:223], v[196:199], v[20:23]
	v_mfma_f32_16x16x32_bf16 v[8:11], v[212:215], v[204:207], v[8:11]
	v_mfma_f32_16x16x32_bf16 v[4:7], v[220:223], v[204:207], v[4:7]
	v_mfma_f32_16x16x32_bf16 v[56:59], v[216:219], v[184:187], v[56:59]
	v_mfma_f32_16x16x32_bf16 v[52:55], v[224:227], v[184:187], v[52:55]
	v_mfma_f32_16x16x32_bf16 v[40:43], v[216:219], v[192:195], v[40:43]
	v_mfma_f32_16x16x32_bf16 v[36:39], v[224:227], v[192:195], v[36:39]
	v_mfma_f32_16x16x32_bf16 v[24:27], v[216:219], v[200:203], v[24:27]
	v_mfma_f32_16x16x32_bf16 v[20:23], v[224:227], v[200:203], v[20:23]
	v_mfma_f32_16x16x32_bf16 v[8:11], v[216:219], v[208:211], v[8:11]
	v_mfma_f32_16x16x32_bf16 v[4:7], v[224:227], v[208:211], v[4:7]
	s_setprio 2
	s_add_i32 s72, 0, 0x18000
	s_barrier
	s_add_u32 s4, s4, 0x4000
	s_addc_u32 s5, s5, 0
	s_mov_b32 m0, s53
	ds_read_b128 v[180:183], v148 offset:32768
	ds_read_b128 v[184:187], v148 offset:33792
	ds_read_b128 v[188:191], v148 offset:34816
	ds_read_b128 v[192:195], v148 offset:35840
	ds_read_b128 v[196:199], v148 offset:36864
	ds_read_b128 v[200:203], v148 offset:37888
	ds_read_b128 v[204:207], v148 offset:38912
	ds_read_b128 v[208:211], v148 offset:39936
	global_load_lds_dwordx4 v132, s[4:5]
	s_mov_b32 m0, s54
	s_nop 0
	global_load_lds_dwordx4 v138, s[4:5]
	s_waitcnt lgkmcnt(8)
	s_barrier
	s_waitcnt lgkmcnt(0)
	s_setprio 0
	v_mfma_f32_16x16x32_bf16 v[128:131], v[140:143], v[180:183], v[128:131]
	v_mfma_f32_16x16x32_bf16 v[124:127], v[154:157], v[180:183], v[124:127]
	v_mfma_f32_16x16x32_bf16 v[112:115], v[140:143], v[188:191], v[112:115]
	v_mfma_f32_16x16x32_bf16 v[108:111], v[154:157], v[188:191], v[108:111]
	v_mfma_f32_16x16x32_bf16 v[96:99], v[140:143], v[196:199], v[96:99]
	v_mfma_f32_16x16x32_bf16 v[92:95], v[154:157], v[196:199], v[92:95]
	v_mfma_f32_16x16x32_bf16 v[80:83], v[140:143], v[204:207], v[80:83]
	v_mfma_f32_16x16x32_bf16 v[76:79], v[154:157], v[204:207], v[76:79]
	v_mfma_f32_16x16x32_bf16 v[128:131], v[150:153], v[184:187], v[128:131]
	v_mfma_f32_16x16x32_bf16 v[124:127], v[176:179], v[184:187], v[124:127]
	v_mfma_f32_16x16x32_bf16 v[112:115], v[150:153], v[192:195], v[112:115]
	v_mfma_f32_16x16x32_bf16 v[108:111], v[176:179], v[192:195], v[108:111]
	v_mfma_f32_16x16x32_bf16 v[96:99], v[150:153], v[200:203], v[96:99]
	v_mfma_f32_16x16x32_bf16 v[92:95], v[176:179], v[200:203], v[92:95]
	s_setprio 3
	s_barrier
	v_mfma_f32_16x16x32_bf16 v[80:83], v[150:153], v[208:211], v[80:83]
	v_mfma_f32_16x16x32_bf16 v[76:79], v[176:179], v[208:211], v[76:79]
	s_setprio 2
	s_add_i32 s73, 0, 0x1c000
	s_add_u32 s4, s48, 0x8000
	s_addc_u32 s5, s49, 0
	s_add_i32 s72, s72, s29
	ds_read_b128 v[212:215], v228 offset:49152
	ds_read_b128 v[216:219], v228 offset:50176
	ds_read_b128 v[220:223], v228 offset:51200
	ds_read_b128 v[224:227], v228 offset:52224
	s_mov_b32 m0, s72
	s_nop 0
	global_load_lds_dwordx4 v132, s[4:5]
	s_add_i32 m0, s72, 0x2000
	s_nop 0
	global_load_lds_dwordx4 v138, s[4:5]
	s_barrier
	s_waitcnt lgkmcnt(0)
	s_setprio 0
	v_mfma_f32_16x16x32_bf16 v[120:123], v[212:215], v[180:183], v[120:123]
	v_mfma_f32_16x16x32_bf16 v[116:119], v[220:223], v[180:183], v[116:119]
	v_mfma_f32_16x16x32_bf16 v[104:107], v[212:215], v[188:191], v[104:107]
	v_mfma_f32_16x16x32_bf16 v[100:103], v[220:223], v[188:191], v[100:103]
	v_mfma_f32_16x16x32_bf16 v[88:91], v[212:215], v[196:199], v[88:91]
	v_mfma_f32_16x16x32_bf16 v[84:87], v[220:223], v[196:199], v[84:87]
	v_mfma_f32_16x16x32_bf16 v[72:75], v[212:215], v[204:207], v[72:75]
	v_mfma_f32_16x16x32_bf16 v[68:71], v[220:223], v[204:207], v[68:71]
	v_mfma_f32_16x16x32_bf16 v[120:123], v[216:219], v[184:187], v[120:123]
	v_mfma_f32_16x16x32_bf16 v[116:119], v[224:227], v[184:187], v[116:119]
	v_mfma_f32_16x16x32_bf16 v[104:107], v[216:219], v[192:195], v[104:107]
	v_mfma_f32_16x16x32_bf16 v[100:103], v[224:227], v[192:195], v[100:103]
	v_mfma_f32_16x16x32_bf16 v[88:91], v[216:219], v[200:203], v[88:91]
	v_mfma_f32_16x16x32_bf16 v[84:87], v[224:227], v[200:203], v[84:87]
	v_mfma_f32_16x16x32_bf16 v[72:75], v[216:219], v[208:211], v[72:75]
	v_mfma_f32_16x16x32_bf16 v[68:71], v[224:227], v[208:211], v[68:71]
	s_setprio 2
	s_mov_b32 m0, s55
	s_barrier
	ds_read_b128 v[180:183], v148 offset:49152
	ds_read_b128 v[184:187], v148 offset:50176
	ds_read_b128 v[188:191], v148 offset:51200
	ds_read_b128 v[192:195], v148 offset:52224
	ds_read_b128 v[196:199], v148 offset:53248
	ds_read_b128 v[200:203], v148 offset:54272
	ds_read_b128 v[204:207], v148 offset:55296
	ds_read_b128 v[208:211], v148 offset:56320
	global_load_lds_dwordx4 v132, s[50:51]
	s_mov_b32 m0, s56
	s_nop 0
	global_load_lds_dwordx4 v138, s[50:51]
	s_waitcnt vmcnt(10)
	s_barrier
	s_waitcnt lgkmcnt(0)
	s_setprio 0
	v_mfma_f32_16x16x32_bf16 v[64:67], v[140:143], v[180:183], v[64:67]
	v_mfma_f32_16x16x32_bf16 v[60:63], v[154:157], v[180:183], v[60:63]
	v_mfma_f32_16x16x32_bf16 v[48:51], v[140:143], v[188:191], v[48:51]
	v_mfma_f32_16x16x32_bf16 v[44:47], v[154:157], v[188:191], v[44:47]
	v_mfma_f32_16x16x32_bf16 v[32:35], v[140:143], v[196:199], v[32:35]
	v_mfma_f32_16x16x32_bf16 v[28:31], v[154:157], v[196:199], v[28:31]
	v_mfma_f32_16x16x32_bf16 v[16:19], v[140:143], v[204:207], v[16:19]
	v_mfma_f32_16x16x32_bf16 v[12:15], v[154:157], v[204:207], v[12:15]
	v_mfma_f32_16x16x32_bf16 v[64:67], v[150:153], v[184:187], v[64:67]
	v_mfma_f32_16x16x32_bf16 v[60:63], v[176:179], v[184:187], v[60:63]
	v_mfma_f32_16x16x32_bf16 v[48:51], v[150:153], v[192:195], v[48:51]
	v_mfma_f32_16x16x32_bf16 v[44:47], v[176:179], v[192:195], v[44:47]
	v_mfma_f32_16x16x32_bf16 v[32:35], v[150:153], v[200:203], v[32:35]
	v_mfma_f32_16x16x32_bf16 v[28:31], v[176:179], v[200:203], v[28:31]
	s_setprio 3
	s_barrier
; #define PG8_STAGE(bufoff, gbase, voff) do { _Pragma("unroll") for (int _i = 0; _i < 2; ++_i) \
;         __builtin_amdgcn_global_load_lds((const unsigned*)((const char*)(gbase) + (voff)[_i]), (LAS unsigned*)(lds + (bufoff) + ldsw + _i * 8192), 16, 0, 0); } while (0)
; #define PG8_MMA(ai, bj, At, Bt) do { __builtin_amdgcn_s_setprio(1); _Pragma("unroll") for (int m = 0; m < 4; ++m) _Pragma("unroll") for (int n = 0; n < 2; ++n) _Pragma("unroll") for (int k = 0; k < 2; ++k) \
;         acc[ai][bj][m][n] = __builtin_amdgcn_mfma_f32_16x16x32_bf16(Bt[n][k], At[m][k], acc[ai][bj][m][n], 0, 0, 0); __builtin_amdgcn_s_setprio(0); } while (0)
; #define PG8_WAIT_V(n) asm volatile("s_waitcnt vmcnt(" #n ")" ::: "memory")
; #define PG8_WAIT_L(n) asm volatile("s_waitcnt lgkmcnt(" #n ")" ::: "memory")
; #define PG8_BAR __builtin_amdgcn_s_barrier()
; #define PG8_SCHED __builtin_amdgcn_sched_barrier(0)
;     __device__ __forceinline__ void operator()(const f32x4 (&acc)[2][2][4][2], const Unit& u, int wr, int wc, int fr, int fq) const {
;     ...
;         } else {
;             float* base = PART + (size_t)u.part * (512 * 2048);
; #pragma unroll
;             for (int ai = 0; ai < 2; ++ai)
; #pragma unroll
;                 for (int m = 0; m < 4; ++m) {
;                     float* rowp = base + (size_t)(row0 - 8192 + ai * HALF + m * 16) * D_MODEL + col0;
; #pragma unroll
;                     for (int bj = 0; bj < 2; ++bj)
; #pragma unroll
;                         for (int n = 0; n < 2; ++n) *(f32x4*)(rowp + bj * HALF + n * 16) = acc[ai][bj][m][n];
;                 }
; template <class Epi, class Sched, int LD>
; __device__ __forceinline__ void gemm_phase(LAS unsigned char* lds, const Gemm g, const Sched& S, const Epi& E) {
;     ...
;             PG8_BAR; PG8_WAIT_L(0); PG8_MMA(1, 0, At, B0); PG8_BAR; PG8_SCHED;
;             PG8_STAGE(PG8_SB(1, 1), b3 + hstep, voffB);
;             PG8_WAIT_V(6); PG8_BAR; PG8_MMA(1, 1, At, B1); PG8_BAR;
;         }
;         E(acc, cur, wr, wc, fr, fq);
;         if (!has_next) break;
	v_mfma_f32_16x16x32_bf16 v[16:19], v[150:153], v[208:211], v[16:19]
	v_mfma_f32_16x16x32_bf16 v[12:15], v[176:179], v[208:211], v[12:15]
	s_setprio 2
	ds_read_b128 v[140:143], v228
	ds_read_b128 v[150:153], v228 offset:1024
	ds_read_b128 v[154:157], v228 offset:2048
	ds_read_b128 v[176:179], v228 offset:3072
	s_add_u32 s4, s48, 0xc000
	s_addc_u32 s5, s49, 0
	s_add_i32 s48, s73, s29
	s_mov_b32 m0, s48
	s_nop 0
	global_load_lds_dwordx4 v132, s[4:5]
	s_add_i32 m0, s48, 0x2000
	s_nop 0
	global_load_lds_dwordx4 v138, s[4:5]
	s_waitcnt vmcnt(6)
	s_barrier
	s_setprio 0
	v_mfma_f32_16x16x32_bf16 v[56:59], v[212:215], v[180:183], v[56:59]
	v_mfma_f32_16x16x32_bf16 v[52:55], v[220:223], v[180:183], v[52:55]
	v_mfma_f32_16x16x32_bf16 v[40:43], v[212:215], v[188:191], v[40:43]
	v_mfma_f32_16x16x32_bf16 v[36:39], v[220:223], v[188:191], v[36:39]
	v_mfma_f32_16x16x32_bf16 v[24:27], v[212:215], v[196:199], v[24:27]
	v_mfma_f32_16x16x32_bf16 v[20:23], v[220:223], v[196:199], v[20:23]
	v_mfma_f32_16x16x32_bf16 v[8:11], v[212:215], v[204:207], v[8:11]
	v_mfma_f32_16x16x32_bf16 v[4:7], v[220:223], v[204:207], v[4:7]
	v_mfma_f32_16x16x32_bf16 v[56:59], v[216:219], v[184:187], v[56:59]
	v_mfma_f32_16x16x32_bf16 v[52:55], v[224:227], v[184:187], v[52:55]
	v_mfma_f32_16x16x32_bf16 v[40:43], v[216:219], v[192:195], v[40:43]
	v_mfma_f32_16x16x32_bf16 v[36:39], v[224:227], v[192:195], v[36:39]
	v_mfma_f32_16x16x32_bf16 v[24:27], v[216:219], v[200:203], v[24:27]
	v_mfma_f32_16x16x32_bf16 v[20:23], v[224:227], v[200:203], v[20:23]
	v_mfma_f32_16x16x32_bf16 v[8:11], v[216:219], v[208:211], v[8:11]
	v_mfma_f32_16x16x32_bf16 v[4:7], v[224:227], v[208:211], v[4:7]
	s_setprio 2
	s_add_u32 s46, s46, 0x10000
	s_addc_u32 s47, s47, 0
	s_add_u32 s69, s69, 0x10000
	s_addc_u32 s70, s70, 0
	s_mov_b32 s4, s71
	s_mov_b32 s32, s71
	s_add_i32 s71, s4, 2
	s_add_u32 s48, s46, 0x4000
	s_addc_u32 s5, s47, 0
	s_cmp_eq_u32 s68, s4
	s_cselect_b32 s4, s42, s48
	s_cselect_b32 s5, s43, s5
	s_cselect_b32 s48, s44, s69
	s_cselect_b32 s49, s45, s70
	s_add_u32 s50, s4, 0x8000
	s_addc_u32 s51, s5, 0
	s_add_i32 s72, 0, 0x10000
	s_cmp_ge_i32 s32, s65
	s_cbranch_scc0 .LBB0_58
	s_barrier
	s_setprio 0
	v_lshl_add_u32 v142, s67, 8, v137
	v_lshl_or_b32 v140, s66, 8, v147
	s_mov_b64 s[4:5], -1
	s_cmp_gt_i32 s18, -1
	v_ashrrev_i32_e32 v141, 31, v140
	v_ashrrev_i32_e32 v143, 31, v142
	s_cbranch_scc0 .LBB0_61
	s_lshl_b64 s[4:5], s[18:19], 22
	v_readlane_b32 s18, v252, 10
	s_add_u32 s4, s18, s4
	v_readlane_b32 s18, v252, 11
	s_addc_u32 s5, s18, s5
	v_lshl_add_u64 v[144:145], v[140:141], 2, s[4:5]
	v_lshlrev_b64 v[150:151], 13, v[142:143]
	s_brev_b32 s4, 63
	v_lshl_add_u64 v[144:145], v[144:145], 0, v[150:151]
	s_mov_b32 s5, -1
	v_lshl_add_u64 v[150:151], v[144:145], 0, s[4:5]
	s_brev_b32 s4, 63
	v_add_co_u32_e32 v152, vcc, s4, v144
	s_mov_b32 s4, 0xfc020000
	s_nop 0
	v_addc_co_u32_e32 v153, vcc, -1, v145, vcc
	s_mov_b32 s5, -1
	global_store_dwordx4 v[152:153], v[128:131], off
	global_store_dwordx4 v[150:151], v[124:127], off offset:64
	global_store_dwordx4 v[150:151], v[120:123], off offset:512
	global_store_dwordx4 v[150:151], v[116:119], off offset:576
	v_lshl_add_u64 v[150:151], v[144:145], 0, s[4:5]
	s_mov_b32 s4, 0xfc020000
	v_add_co_u32_e32 v152, vcc, s4, v144
	s_mov_b32 s4, 0xfc040000
	s_nop 0
	v_addc_co_u32_e32 v153, vcc, -1, v145, vcc
	s_mov_b32 s5, -1
	global_store_dwordx4 v[152:153], v[112:115], off
	global_store_dwordx4 v[150:151], v[108:111], off offset:64
	global_store_dwordx4 v[150:151], v[104:107], off offset:512
	global_store_dwordx4 v[150:151], v[100:103], off offset:576
	v_lshl_add_u64 v[150:151], v[144:145], 0, s[4:5]
	s_mov_b32 s4, 0xfc040000
	v_add_co_u32_e32 v152, vcc, s4, v144
	s_mov_b32 s4, 0xfc060000
	s_nop 0
	v_addc_co_u32_e32 v153, vcc, -1, v145, vcc
	s_mov_b32 s5, -1
	global_store_dwordx4 v[152:153], v[96:99], off
	global_store_dwordx4 v[150:151], v[92:95], off offset:64
	global_store_dwordx4 v[150:151], v[88:91], off offset:512
	global_store_dwordx4 v[150:151], v[84:87], off offset:576
	v_lshl_add_u64 v[150:151], v[144:145], 0, s[4:5]
	s_mov_b32 s4, 0xfc060000
	v_add_co_u32_e32 v152, vcc, s4, v144
	s_mov_b32 s4, 0xfc100000
	s_nop 0
	v_addc_co_u32_e32 v153, vcc, -1, v145, vcc
	s_mov_b32 s5, -1
	global_store_dwordx4 v[152:153], v[80:83], off
	global_store_dwordx4 v[150:151], v[76:79], off offset:64
	global_store_dwordx4 v[150:151], v[72:75], off offset:512
	global_store_dwordx4 v[150:151], v[68:71], off offset:576
	v_lshl_add_u64 v[150:151], v[144:145], 0, s[4:5]
	s_mov_b32 s4, 0xfc100000
	v_add_co_u32_e32 v152, vcc, s4, v144
	s_mov_b32 s4, 0xfc120000
	s_nop 0
	v_addc_co_u32_e32 v153, vcc, -1, v145, vcc
	s_mov_b32 s5, -1
	global_store_dwordx4 v[152:153], v[64:67], off
	global_store_dwordx4 v[150:151], v[60:63], off offset:64
	global_store_dwordx4 v[150:151], v[56:59], off offset:512
	global_store_dwordx4 v[150:151], v[52:55], off offset:576
	v_lshl_add_u64 v[150:151], v[144:145], 0, s[4:5]
	s_mov_b32 s4, 0xfc120000
	v_add_co_u32_e32 v152, vcc, s4, v144
	s_mov_b32 s4, 0xfc140000
	s_nop 0
	v_addc_co_u32_e32 v153, vcc, -1, v145, vcc
	s_mov_b32 s5, -1
	global_store_dwordx4 v[152:153], v[48:51], off
	global_store_dwordx4 v[150:151], v[44:47], off offset:64
	global_store_dwordx4 v[150:151], v[40:43], off offset:512
	global_store_dwordx4 v[150:151], v[36:39], off offset:576
	v_lshl_add_u64 v[150:151], v[144:145], 0, s[4:5]
	s_mov_b32 s4, 0xfc140000
	v_add_co_u32_e32 v152, vcc, s4, v144
	s_mov_b32 s4, 0xfc160000
	s_nop 0
	v_addc_co_u32_e32 v153, vcc, -1, v145, vcc
	s_mov_b32 s5, -1
	global_store_dwordx4 v[152:153], v[32:35], off
	global_store_dwordx4 v[150:151], v[28:31], off offset:64
	global_store_dwordx4 v[150:151], v[24:27], off offset:512
	global_store_dwordx4 v[150:151], v[20:23], off offset:576
	v_lshl_add_u64 v[150:151], v[144:145], 0, s[4:5]
	v_add_co_u32_e32 v144, vcc, 0xfc160000, v144
	s_mov_b64 s[4:5], 0
	s_nop 0
	v_addc_co_u32_e32 v145, vcc, -1, v145, vcc
	global_store_dwordx4 v[144:145], v[16:19], off
	global_store_dwordx4 v[150:151], v[12:15], off offset:64
	global_store_dwordx4 v[150:151], v[8:11], off offset:512
	global_store_dwordx4 v[150:151], v[4:7], off offset:576

; #define PG8_STAGE(bufoff, gbase, voff) do { _Pragma("unroll") for (int _i = 0; _i < 2; ++_i) \
;         __builtin_amdgcn_global_load_lds((const unsigned*)((const char*)(gbase) + (voff)[_i]), (LAS unsigned*)(lds + (bufoff) + ldsw + _i * 8192), 16, 0, 0); } while (0)
; #define PG8_LDA(dst, b, h) do { _Pragma("unroll") for (int m = 0; m < 4; ++m) _Pragma("unroll") for (int k = 0; k < 2; ++k) dst[m][k] = *(const LAS bf16x8*)(lds + PG8_SA(b, h) + aoff + m * 2048 + k * 1024); } while (0)
; #define PG8_LDB(dst, b, h) do { _Pragma("unroll") for (int n = 0; n < 2; ++n) _Pragma("unroll") for (int k = 0; k < 2; ++k) dst[n][k] = *(const LAS bf16x8*)(lds + PG8_SB(b, h) + boff + n * 2048 + k * 1024); } while (0)
; #define PG8_SCHED __builtin_amdgcn_sched_barrier(0)
; template <class Epi, class Sched, int LD>
; __device__ __forceinline__ void gemm_phase(LAS unsigned char* lds, const Gemm g, const Sched& S, const Epi& E) {
;     ...
;         const bool has_next = S.next(ui + 1, nxt);
;         const char* nA = has_next ? (const char*)g.A + (size_t)nxt.pm * tstep + (size_t)(nxt.kofs / BK) * kstep : cA; const char* nB = has_next ? (const char*)g.Bt + (size_t)nxt.pn * tstep + (size_t)(nxt.kofs / BK) * kstep : cB;
;         const int nt = cur.nt;
;         for (int t = 0; t < nt; t += 2) {
;             const bool last = (t == nt - 2);
;             const char* a1 = cA + (size_t)(t + 1) * kstep;
;             const char* a2 = last ? nA : cA + (size_t)(t + 2) * kstep; const char* b2 = last ? nB : cB + (size_t)(t + 2) * kstep;
;             const char* a3 = a2 + kstep; const char* b3 = b2 + kstep;
;             PG8_LDB(B0, 0, 0); PG8_SCHED; PG8_LDA(At, 0, 0); PG8_STAGE(PG8_SA(1, 1), a1 + hstep, voffA);
;     ...
;         for (int a = 0; a < 2; ++a)
; #pragma unroll
;             for (int b = 0; b < 2; ++b)
; #pragma unroll
;                 for (int m = 0; m < 4; ++m)
; #pragma unroll
;                     for (int n = 0; n < 2; ++n) acc[a][b][m][n] = (f32x4){0.f, 0.f, 0.f, 0.f};
;         cur = nxt; cA = nA; cB = nB; ++ui;
.LBB0_500:
	s_add_u32 s54, s4, 0xc000
	s_addc_u32 s55, s5, 0
	s_add_u32 s29, s56, 0x10000
	v_mov_b32_e32 v4, 0
	s_addc_u32 s47, s57, 0
	s_mov_b32 s49, -2
	v_mov_b32_e32 v5, v4
	v_mov_b32_e32 v6, v4
	v_mov_b32_e32 v7, v4
	v_mov_b32_e32 v8, v4
	v_mov_b32_e32 v9, v4
	v_mov_b32_e32 v10, v4
	v_mov_b32_e32 v11, v4
	v_mov_b32_e32 v12, v4
	v_mov_b32_e32 v13, v4
	v_mov_b32_e32 v14, v4
	v_mov_b32_e32 v15, v4
	v_mov_b32_e32 v16, v4
	v_mov_b32_e32 v17, v4
	v_mov_b32_e32 v18, v4
	v_mov_b32_e32 v19, v4
	v_mov_b32_e32 v28, v4
	v_mov_b32_e32 v29, v4
	v_mov_b32_e32 v30, v4
	v_mov_b32_e32 v31, v4
	v_mov_b32_e32 v32, v4
	v_mov_b32_e32 v33, v4
	v_mov_b32_e32 v34, v4
	v_mov_b32_e32 v35, v4
	v_mov_b32_e32 v44, v4
	v_mov_b32_e32 v45, v4
	v_mov_b32_e32 v46, v4
	v_mov_b32_e32 v47, v4
	v_mov_b32_e32 v48, v4
	v_mov_b32_e32 v49, v4
	v_mov_b32_e32 v50, v4
	v_mov_b32_e32 v51, v4
	v_mov_b32_e32 v20, v4
	v_mov_b32_e32 v21, v4
	v_mov_b32_e32 v22, v4
	v_mov_b32_e32 v23, v4
	v_mov_b32_e32 v24, v4
	v_mov_b32_e32 v25, v4
	v_mov_b32_e32 v26, v4
	v_mov_b32_e32 v27, v4
	v_mov_b32_e32 v36, v4
	v_mov_b32_e32 v37, v4
	v_mov_b32_e32 v38, v4
	v_mov_b32_e32 v39, v4
	v_mov_b32_e32 v40, v4
	v_mov_b32_e32 v41, v4
	v_mov_b32_e32 v42, v4
	v_mov_b32_e32 v43, v4
	v_mov_b32_e32 v52, v4
	v_mov_b32_e32 v53, v4
	v_mov_b32_e32 v54, v4
	v_mov_b32_e32 v55, v4
	v_mov_b32_e32 v56, v4
	v_mov_b32_e32 v57, v4
	v_mov_b32_e32 v58, v4
	v_mov_b32_e32 v59, v4
	v_mov_b32_e32 v60, v4
	v_mov_b32_e32 v61, v4
	v_mov_b32_e32 v62, v4
	v_mov_b32_e32 v63, v4
	v_mov_b32_e32 v64, v4
	v_mov_b32_e32 v65, v4
	v_mov_b32_e32 v66, v4
	v_mov_b32_e32 v67, v4
	v_mov_b32_e32 v68, v4
	v_mov_b32_e32 v69, v4
	v_mov_b32_e32 v70, v4
	v_mov_b32_e32 v71, v4
	v_mov_b32_e32 v72, v4
	v_mov_b32_e32 v73, v4
	v_mov_b32_e32 v74, v4
	v_mov_b32_e32 v75, v4
	v_mov_b32_e32 v76, v4
	v_mov_b32_e32 v77, v4
	v_mov_b32_e32 v78, v4
	v_mov_b32_e32 v79, v4
	v_mov_b32_e32 v80, v4
	v_mov_b32_e32 v81, v4
	v_mov_b32_e32 v82, v4
	v_mov_b32_e32 v83, v4
	v_mov_b32_e32 v92, v4
	v_mov_b32_e32 v93, v4
	v_mov_b32_e32 v94, v4
	v_mov_b32_e32 v95, v4
	v_mov_b32_e32 v96, v4
	v_mov_b32_e32 v97, v4
	v_mov_b32_e32 v98, v4
	v_mov_b32_e32 v99, v4
	v_mov_b32_e32 v108, v4
	v_mov_b32_e32 v109, v4
	v_mov_b32_e32 v110, v4
	v_mov_b32_e32 v111, v4
	v_mov_b32_e32 v112, v4
	v_mov_b32_e32 v113, v4
	v_mov_b32_e32 v114, v4
	v_mov_b32_e32 v115, v4
	v_mov_b32_e32 v84, v4
	v_mov_b32_e32 v85, v4
	v_mov_b32_e32 v86, v4
	v_mov_b32_e32 v87, v4
	v_mov_b32_e32 v88, v4
	v_mov_b32_e32 v89, v4
	v_mov_b32_e32 v90, v4
	v_mov_b32_e32 v91, v4
	v_mov_b32_e32 v100, v4
	v_mov_b32_e32 v101, v4
	v_mov_b32_e32 v102, v4
	v_mov_b32_e32 v103, v4
	v_mov_b32_e32 v104, v4
	v_mov_b32_e32 v105, v4
	v_mov_b32_e32 v106, v4
	v_mov_b32_e32 v107, v4
	v_mov_b32_e32 v116, v4
	v_mov_b32_e32 v117, v4
	v_mov_b32_e32 v118, v4
	v_mov_b32_e32 v119, v4
	v_mov_b32_e32 v120, v4
	v_mov_b32_e32 v121, v4
	v_mov_b32_e32 v122, v4
	v_mov_b32_e32 v123, v4
	v_mov_b32_e32 v124, v4
	v_mov_b32_e32 v125, v4
	v_mov_b32_e32 v126, v4
	v_mov_b32_e32 v127, v4
	v_mov_b32_e32 v128, v4
	v_mov_b32_e32 v129, v4
	v_mov_b32_e32 v130, v4
	v_mov_b32_e32 v131, v4
	ds_read_b128 v[148:151], v228
	ds_read_b128 v[152:155], v228 offset:1024
	ds_read_b128 v[156:159], v228 offset:2048
	ds_read_b128 v[176:179], v228 offset:3072
	s_add_u32 s4, s54, 0x4000
	s_addc_u32 s5, s55, 0
	s_cmp_eq_u32 s49, 28
	s_cselect_b32 s4, s50, s4
	s_cselect_b32 s5, s51, s5
	s_cselect_b32 s56, s40, s29
	s_cselect_b32 s57, s41, s47
	s_add_u32 s58, s4, 0x8000
	s_addc_u32 s59, s5, 0
	s_add_i32 s69, 0, 0x10000
	s_branch .Lrot_inp_body

; #define PG8_STAGE(bufoff, gbase, voff) do { _Pragma("unroll") for (int _i = 0; _i < 2; ++_i) \
;         __builtin_amdgcn_global_load_lds((const unsigned*)((const char*)(gbase) + (voff)[_i]), (LAS unsigned*)(lds + (bufoff) + ldsw + _i * 8192), 16, 0, 0); } while (0)
; #define PG8_LDA(dst, b, h) do { _Pragma("unroll") for (int m = 0; m < 4; ++m) _Pragma("unroll") for (int k = 0; k < 2; ++k) dst[m][k] = *(const LAS bf16x8*)(lds + PG8_SA(b, h) + aoff + m * 2048 + k * 1024); } while (0)
; #define PG8_LDB(dst, b, h) do { _Pragma("unroll") for (int n = 0; n < 2; ++n) _Pragma("unroll") for (int k = 0; k < 2; ++k) dst[n][k] = *(const LAS bf16x8*)(lds + PG8_SB(b, h) + boff + n * 2048 + k * 1024); } while (0)
; #define PG8_MMA(ai, bj, At, Bt) do { __builtin_amdgcn_s_setprio(1); _Pragma("unroll") for (int m = 0; m < 4; ++m) _Pragma("unroll") for (int n = 0; n < 2; ++n) _Pragma("unroll") for (int k = 0; k < 2; ++k) \
;         acc[ai][bj][m][n] = __builtin_amdgcn_mfma_f32_16x16x32_bf16(Bt[n][k], At[m][k], acc[ai][bj][m][n], 0, 0, 0); __builtin_amdgcn_s_setprio(0); } while (0)
; #define PG8_WAIT_V(n) asm volatile("s_waitcnt vmcnt(" #n ")" ::: "memory")
; #define PG8_WAIT_L(n) asm volatile("s_waitcnt lgkmcnt(" #n ")" ::: "memory")
; #define PG8_BAR __builtin_amdgcn_s_barrier()
; #define PG8_SCHED __builtin_amdgcn_sched_barrier(0)
; template <class Epi, class Sched, int LD>
; __device__ __forceinline__ void gemm_phase(LAS unsigned char* lds, const Gemm g, const Sched& S, const Epi& E) {
;     ...
;             PG8_LDB(B0, 0, 0); PG8_SCHED; PG8_LDA(At, 0, 0); PG8_STAGE(PG8_SA(1, 1), a1 + hstep, voffA);
;             PG8_WAIT_L(8); PG8_BAR; PG8_WAIT_L(0); PG8_MMA(0, 0, At, B0); PG8_BAR; PG8_SCHED;
;             PG8_LDB(B1, 0, 1); PG8_STAGE(PG8_SB(0, 0), b2, voffB);
;             PG8_BAR; PG8_WAIT_L(0); PG8_MMA(0, 1, At, B1); PG8_BAR;
;             PG8_LDA(At, 0, 1); PG8_STAGE(PG8_SA(0, 0), a2, voffA);
;             PG8_BAR; PG8_WAIT_L(0); PG8_MMA(1, 0, At, B0); PG8_BAR; PG8_SCHED;
;             PG8_STAGE(PG8_SB(0, 1), b2 + hstep, voffB);
;             PG8_WAIT_V(6); PG8_BAR; PG8_MMA(1, 1, At, B1); PG8_BAR;
;             PG8_LDB(B0, 1, 0); PG8_SCHED; PG8_LDA(At, 1, 0); PG8_STAGE(PG8_SA(0, 1), a2 + hstep, voffA);
.Lrot_inp_body:
	s_add_i32 m0, s52, 0xc000
	ds_read_b128 v[180:183], v146
	ds_read_b128 v[184:187], v146 offset:1024
	ds_read_b128 v[188:191], v146 offset:2048
	ds_read_b128 v[192:195], v146 offset:3072
	ds_read_b128 v[196:199], v146 offset:4096
	ds_read_b128 v[200:203], v146 offset:5120
	ds_read_b128 v[204:207], v146 offset:6144
	ds_read_b128 v[208:211], v146 offset:7168
	global_load_lds_dwordx4 v132, s[54:55]
	s_add_i32 m0, s52, 0xe000
	s_nop 0
	global_load_lds_dwordx4 v138, s[54:55]
	s_waitcnt lgkmcnt(8)
	s_barrier
	s_waitcnt lgkmcnt(0)
	s_setprio 0
	v_mfma_f32_16x16x32_bf16 v[128:131], v[148:151], v[180:183], v[128:131]
	v_mfma_f32_16x16x32_bf16 v[124:127], v[156:159], v[180:183], v[124:127]
	v_mfma_f32_16x16x32_bf16 v[120:123], v[148:151], v[188:191], v[120:123]
	v_mfma_f32_16x16x32_bf16 v[116:119], v[156:159], v[188:191], v[116:119]
	v_mfma_f32_16x16x32_bf16 v[104:107], v[148:151], v[196:199], v[104:107]
	v_mfma_f32_16x16x32_bf16 v[100:103], v[156:159], v[196:199], v[100:103]
	v_mfma_f32_16x16x32_bf16 v[88:91], v[148:151], v[204:207], v[88:91]
	v_mfma_f32_16x16x32_bf16 v[84:87], v[156:159], v[204:207], v[84:87]
	v_mfma_f32_16x16x32_bf16 v[128:131], v[152:155], v[184:187], v[128:131]
	v_mfma_f32_16x16x32_bf16 v[124:127], v[176:179], v[184:187], v[124:127]
	v_mfma_f32_16x16x32_bf16 v[120:123], v[152:155], v[192:195], v[120:123]
	v_mfma_f32_16x16x32_bf16 v[116:119], v[176:179], v[192:195], v[116:119]
	v_mfma_f32_16x16x32_bf16 v[104:107], v[152:155], v[200:203], v[104:107]
	v_mfma_f32_16x16x32_bf16 v[100:103], v[176:179], v[200:203], v[100:103]
	s_setprio 3
	s_barrier
	v_mfma_f32_16x16x32_bf16 v[88:91], v[152:155], v[208:211], v[88:91]
	v_mfma_f32_16x16x32_bf16 v[84:87], v[176:179], v[208:211], v[84:87]
	s_setprio 2
	s_add_i32 s72, 0, 0x14000
	s_add_i32 s69, s69, s39
	ds_read_b128 v[212:215], v228 offset:16384
	ds_read_b128 v[216:219], v228 offset:17408
	ds_read_b128 v[220:223], v228 offset:18432
	ds_read_b128 v[224:227], v228 offset:19456
	s_mov_b32 m0, s69
	s_nop 0
	global_load_lds_dwordx4 v132, s[56:57]
	s_add_i32 m0, s69, 0x2000
	s_nop 0
	global_load_lds_dwordx4 v138, s[56:57]
	s_barrier
	s_waitcnt lgkmcnt(0)
	s_setprio 0
	v_mfma_f32_16x16x32_bf16 v[112:115], v[212:215], v[180:183], v[112:115]
	v_mfma_f32_16x16x32_bf16 v[108:111], v[220:223], v[180:183], v[108:111]
	v_mfma_f32_16x16x32_bf16 v[96:99], v[212:215], v[188:191], v[96:99]
	v_mfma_f32_16x16x32_bf16 v[92:95], v[220:223], v[188:191], v[92:95]
	v_mfma_f32_16x16x32_bf16 v[80:83], v[212:215], v[196:199], v[80:83]
	v_mfma_f32_16x16x32_bf16 v[76:79], v[220:223], v[196:199], v[76:79]
	v_mfma_f32_16x16x32_bf16 v[72:75], v[212:215], v[204:207], v[72:75]
	v_mfma_f32_16x16x32_bf16 v[68:71], v[220:223], v[204:207], v[68:71]
	v_mfma_f32_16x16x32_bf16 v[112:115], v[216:219], v[184:187], v[112:115]
	v_mfma_f32_16x16x32_bf16 v[108:111], v[224:227], v[184:187], v[108:111]
	v_mfma_f32_16x16x32_bf16 v[96:99], v[216:219], v[192:195], v[96:99]
	v_mfma_f32_16x16x32_bf16 v[92:95], v[224:227], v[192:195], v[92:95]
	v_mfma_f32_16x16x32_bf16 v[80:83], v[216:219], v[200:203], v[80:83]
	v_mfma_f32_16x16x32_bf16 v[76:79], v[224:227], v[200:203], v[76:79]
	v_mfma_f32_16x16x32_bf16 v[72:75], v[216:219], v[208:211], v[72:75]
	v_mfma_f32_16x16x32_bf16 v[68:71], v[224:227], v[208:211], v[68:71]
	s_setprio 2
	s_mov_b32 m0, s52
	s_barrier
	ds_read_b128 v[180:183], v146 offset:16384
	ds_read_b128 v[184:187], v146 offset:17408
	ds_read_b128 v[188:191], v146 offset:18432
	ds_read_b128 v[192:195], v146 offset:19456
	ds_read_b128 v[196:199], v146 offset:20480
	ds_read_b128 v[200:203], v146 offset:21504
	ds_read_b128 v[204:207], v146 offset:22528
	ds_read_b128 v[208:211], v146 offset:23552
	global_load_lds_dwordx4 v132, s[4:5]
	s_mov_b32 m0, s53
	s_nop 0
	global_load_lds_dwordx4 v138, s[4:5]
	s_waitcnt vmcnt(10)
	s_barrier
	s_waitcnt lgkmcnt(0)
	s_setprio 0
	v_mfma_f32_16x16x32_bf16 v[64:67], v[148:151], v[180:183], v[64:67]
	v_mfma_f32_16x16x32_bf16 v[60:63], v[156:159], v[180:183], v[60:63]
	v_mfma_f32_16x16x32_bf16 v[56:59], v[148:151], v[188:191], v[56:59]
	v_mfma_f32_16x16x32_bf16 v[52:55], v[156:159], v[188:191], v[52:55]
	v_mfma_f32_16x16x32_bf16 v[40:43], v[148:151], v[196:199], v[40:43]
	v_mfma_f32_16x16x32_bf16 v[36:39], v[156:159], v[196:199], v[36:39]
	v_mfma_f32_16x16x32_bf16 v[24:27], v[148:151], v[204:207], v[24:27]
	v_mfma_f32_16x16x32_bf16 v[20:23], v[156:159], v[204:207], v[20:23]
	v_mfma_f32_16x16x32_bf16 v[64:67], v[152:155], v[184:187], v[64:67]
	v_mfma_f32_16x16x32_bf16 v[60:63], v[176:179], v[184:187], v[60:63]
	v_mfma_f32_16x16x32_bf16 v[56:59], v[152:155], v[192:195], v[56:59]
	v_mfma_f32_16x16x32_bf16 v[52:55], v[176:179], v[192:195], v[52:55]
	v_mfma_f32_16x16x32_bf16 v[40:43], v[152:155], v[200:203], v[40:43]
	v_mfma_f32_16x16x32_bf16 v[36:39], v[176:179], v[200:203], v[36:39]
	s_setprio 3
	s_barrier
	v_mfma_f32_16x16x32_bf16 v[24:27], v[152:155], v[208:211], v[24:27]
	v_mfma_f32_16x16x32_bf16 v[20:23], v[176:179], v[208:211], v[20:23]
	s_setprio 2
	ds_read_b128 v[148:151], v228 offset:32768
	ds_read_b128 v[152:155], v228 offset:33792
	ds_read_b128 v[156:159], v228 offset:34816
	ds_read_b128 v[176:179], v228 offset:35840
	s_add_u32 s70, s56, 0x4000
	s_addc_u32 s71, s57, 0
	s_add_i32 s69, s72, s39
	s_mov_b32 m0, s69
	s_nop 0
	global_load_lds_dwordx4 v132, s[70:71]
	s_add_i32 m0, s69, 0x2000
	s_nop 0
	global_load_lds_dwordx4 v138, s[70:71]
	s_waitcnt vmcnt(6)
	s_barrier
; #define PG8_STAGE(bufoff, gbase, voff) do { _Pragma("unroll") for (int _i = 0; _i < 2; ++_i) \
;         __builtin_amdgcn_global_load_lds((const unsigned*)((const char*)(gbase) + (voff)[_i]), (LAS unsigned*)(lds + (bufoff) + ldsw + _i * 8192), 16, 0, 0); } while (0)
; #define PG8_LDA(dst, b, h) do { _Pragma("unroll") for (int m = 0; m < 4; ++m) _Pragma("unroll") for (int k = 0; k < 2; ++k) dst[m][k] = *(const LAS bf16x8*)(lds + PG8_SA(b, h) + aoff + m * 2048 + k * 1024); } while (0)
; #define PG8_LDB(dst, b, h) do { _Pragma("unroll") for (int n = 0; n < 2; ++n) _Pragma("unroll") for (int k = 0; k < 2; ++k) dst[n][k] = *(const LAS bf16x8*)(lds + PG8_SB(b, h) + boff + n * 2048 + k * 1024); } while (0)
; #define PG8_MMA(ai, bj, At, Bt) do { __builtin_amdgcn_s_setprio(1); _Pragma("unroll") for (int m = 0; m < 4; ++m) _Pragma("unroll") for (int n = 0; n < 2; ++n) _Pragma("unroll") for (int k = 0; k < 2; ++k) \
;         acc[ai][bj][m][n] = __builtin_amdgcn_mfma_f32_16x16x32_bf16(Bt[n][k], At[m][k], acc[ai][bj][m][n], 0, 0, 0); __builtin_amdgcn_s_setprio(0); } while (0)
; #define PG8_WAIT_V(n) asm volatile("s_waitcnt vmcnt(" #n ")" ::: "memory")
; #define PG8_WAIT_L(n) asm volatile("s_waitcnt lgkmcnt(" #n ")" ::: "memory")
; #define PG8_BAR __builtin_amdgcn_s_barrier()
; #define PG8_SCHED __builtin_amdgcn_sched_barrier(0)
; template <class Epi, class Sched, int LD>
; __device__ __forceinline__ void gemm_phase(LAS unsigned char* lds, const Gemm g, const Sched& S, const Epi& E) {
;     ...
;             PG8_WAIT_V(6); PG8_BAR; PG8_MMA(1, 1, At, B1); PG8_BAR;
;             PG8_LDB(B0, 1, 0); PG8_SCHED; PG8_LDA(At, 1, 0); PG8_STAGE(PG8_SA(0, 1), a2 + hstep, voffA);
;             PG8_WAIT_L(8); PG8_BAR; PG8_WAIT_L(0); PG8_MMA(0, 0, At, B0); PG8_BAR; PG8_SCHED;
;             PG8_LDB(B1, 1, 1); PG8_STAGE(PG8_SB(1, 0), b3, voffB);
;             PG8_BAR; PG8_WAIT_L(0); PG8_MMA(0, 1, At, B1); PG8_BAR;
;             PG8_LDA(At, 1, 1); PG8_STAGE(PG8_SA(1, 0), a3, voffA);
;             PG8_BAR; PG8_WAIT_L(0); PG8_MMA(1, 0, At, B0); PG8_BAR; PG8_SCHED;
	s_setprio 0
	v_mfma_f32_16x16x32_bf16 v[48:51], v[212:215], v[180:183], v[48:51]
	v_mfma_f32_16x16x32_bf16 v[44:47], v[220:223], v[180:183], v[44:47]
	v_mfma_f32_16x16x32_bf16 v[32:35], v[212:215], v[188:191], v[32:35]
	v_mfma_f32_16x16x32_bf16 v[28:31], v[220:223], v[188:191], v[28:31]
	v_mfma_f32_16x16x32_bf16 v[16:19], v[212:215], v[196:199], v[16:19]
	v_mfma_f32_16x16x32_bf16 v[12:15], v[220:223], v[196:199], v[12:15]
	v_mfma_f32_16x16x32_bf16 v[8:11], v[212:215], v[204:207], v[8:11]
	v_mfma_f32_16x16x32_bf16 v[4:7], v[220:223], v[204:207], v[4:7]
	v_mfma_f32_16x16x32_bf16 v[48:51], v[216:219], v[184:187], v[48:51]
	v_mfma_f32_16x16x32_bf16 v[44:47], v[224:227], v[184:187], v[44:47]
	v_mfma_f32_16x16x32_bf16 v[32:35], v[216:219], v[192:195], v[32:35]
	v_mfma_f32_16x16x32_bf16 v[28:31], v[224:227], v[192:195], v[28:31]
	v_mfma_f32_16x16x32_bf16 v[16:19], v[216:219], v[200:203], v[16:19]
	v_mfma_f32_16x16x32_bf16 v[12:15], v[224:227], v[200:203], v[12:15]
	v_mfma_f32_16x16x32_bf16 v[8:11], v[216:219], v[208:211], v[8:11]
	v_mfma_f32_16x16x32_bf16 v[4:7], v[224:227], v[208:211], v[4:7]
	s_setprio 2
	s_add_i32 s69, 0, 0x18000
	s_barrier
	s_add_u32 s4, s4, 0x4000
	s_addc_u32 s5, s5, 0
	s_mov_b32 m0, s60
	ds_read_b128 v[180:183], v146 offset:32768
	ds_read_b128 v[184:187], v146 offset:33792
	ds_read_b128 v[188:191], v146 offset:34816
	ds_read_b128 v[192:195], v146 offset:35840
	ds_read_b128 v[196:199], v146 offset:36864
	ds_read_b128 v[200:203], v146 offset:37888
	ds_read_b128 v[204:207], v146 offset:38912
	ds_read_b128 v[208:211], v146 offset:39936
	global_load_lds_dwordx4 v132, s[4:5]
	s_mov_b32 m0, s61
	s_nop 0
	global_load_lds_dwordx4 v138, s[4:5]
	s_waitcnt lgkmcnt(8)
	s_barrier
	s_waitcnt lgkmcnt(0)
	s_setprio 0
	v_mfma_f32_16x16x32_bf16 v[128:131], v[148:151], v[180:183], v[128:131]
	v_mfma_f32_16x16x32_bf16 v[124:127], v[156:159], v[180:183], v[124:127]
	v_mfma_f32_16x16x32_bf16 v[120:123], v[148:151], v[188:191], v[120:123]
	v_mfma_f32_16x16x32_bf16 v[116:119], v[156:159], v[188:191], v[116:119]
	v_mfma_f32_16x16x32_bf16 v[104:107], v[148:151], v[196:199], v[104:107]
	v_mfma_f32_16x16x32_bf16 v[100:103], v[156:159], v[196:199], v[100:103]
	v_mfma_f32_16x16x32_bf16 v[88:91], v[148:151], v[204:207], v[88:91]
	v_mfma_f32_16x16x32_bf16 v[84:87], v[156:159], v[204:207], v[84:87]
	v_mfma_f32_16x16x32_bf16 v[128:131], v[152:155], v[184:187], v[128:131]
	v_mfma_f32_16x16x32_bf16 v[124:127], v[176:179], v[184:187], v[124:127]
	v_mfma_f32_16x16x32_bf16 v[120:123], v[152:155], v[192:195], v[120:123]
	v_mfma_f32_16x16x32_bf16 v[116:119], v[176:179], v[192:195], v[116:119]
	v_mfma_f32_16x16x32_bf16 v[104:107], v[152:155], v[200:203], v[104:107]
	v_mfma_f32_16x16x32_bf16 v[100:103], v[176:179], v[200:203], v[100:103]
	s_setprio 3
	s_barrier
	v_mfma_f32_16x16x32_bf16 v[88:91], v[152:155], v[208:211], v[88:91]
	v_mfma_f32_16x16x32_bf16 v[84:87], v[176:179], v[208:211], v[84:87]
	s_setprio 2
	s_add_i32 s70, 0, 0x1c000
	s_add_u32 s4, s56, 0x8000
	s_addc_u32 s5, s57, 0
	s_add_i32 s69, s69, s39
	ds_read_b128 v[212:215], v228 offset:49152
	ds_read_b128 v[216:219], v228 offset:50176
	ds_read_b128 v[220:223], v228 offset:51200
	ds_read_b128 v[224:227], v228 offset:52224
	s_mov_b32 m0, s69
	s_nop 0
	global_load_lds_dwordx4 v132, s[4:5]
	s_add_i32 m0, s69, 0x2000
	s_nop 0
	global_load_lds_dwordx4 v138, s[4:5]
	s_barrier
	s_waitcnt lgkmcnt(0)
	s_setprio 0
	v_mfma_f32_16x16x32_bf16 v[112:115], v[212:215], v[180:183], v[112:115]
	v_mfma_f32_16x16x32_bf16 v[108:111], v[220:223], v[180:183], v[108:111]
	v_mfma_f32_16x16x32_bf16 v[96:99], v[212:215], v[188:191], v[96:99]
	v_mfma_f32_16x16x32_bf16 v[92:95], v[220:223], v[188:191], v[92:95]
	v_mfma_f32_16x16x32_bf16 v[80:83], v[212:215], v[196:199], v[80:83]
	v_mfma_f32_16x16x32_bf16 v[76:79], v[220:223], v[196:199], v[76:79]
	v_mfma_f32_16x16x32_bf16 v[72:75], v[212:215], v[204:207], v[72:75]
	v_mfma_f32_16x16x32_bf16 v[68:71], v[220:223], v[204:207], v[68:71]
	v_mfma_f32_16x16x32_bf16 v[112:115], v[216:219], v[184:187], v[112:115]
	v_mfma_f32_16x16x32_bf16 v[108:111], v[224:227], v[184:187], v[108:111]
	v_mfma_f32_16x16x32_bf16 v[96:99], v[216:219], v[192:195], v[96:99]
	v_mfma_f32_16x16x32_bf16 v[92:95], v[224:227], v[192:195], v[92:95]
	v_mfma_f32_16x16x32_bf16 v[80:83], v[216:219], v[200:203], v[80:83]
	v_mfma_f32_16x16x32_bf16 v[76:79], v[224:227], v[200:203], v[76:79]
	v_mfma_f32_16x16x32_bf16 v[72:75], v[216:219], v[208:211], v[72:75]
	v_mfma_f32_16x16x32_bf16 v[68:71], v[224:227], v[208:211], v[68:71]
	s_setprio 2
	s_mov_b32 m0, s64
	s_barrier
	ds_read_b128 v[180:183], v146 offset:49152
	ds_read_b128 v[184:187], v146 offset:50176
	ds_read_b128 v[188:191], v146 offset:51200
	ds_read_b128 v[192:195], v146 offset:52224
	ds_read_b128 v[196:199], v146 offset:53248
	ds_read_b128 v[200:203], v146 offset:54272
	ds_read_b128 v[204:207], v146 offset:55296
	ds_read_b128 v[208:211], v146 offset:56320
	global_load_lds_dwordx4 v132, s[58:59]
	s_mov_b32 m0, s65
	s_nop 0
	global_load_lds_dwordx4 v138, s[58:59]
	s_waitcnt vmcnt(10)
	s_barrier
; #define PG8_STAGE(bufoff, gbase, voff) do { _Pragma("unroll") for (int _i = 0; _i < 2; ++_i) \
;         __builtin_amdgcn_global_load_lds((const unsigned*)((const char*)(gbase) + (voff)[_i]), (LAS unsigned*)(lds + (bufoff) + ldsw + _i * 8192), 16, 0, 0); } while (0)
; #define PG8_MMA(ai, bj, At, Bt) do { __builtin_amdgcn_s_setprio(1); _Pragma("unroll") for (int m = 0; m < 4; ++m) _Pragma("unroll") for (int n = 0; n < 2; ++n) _Pragma("unroll") for (int k = 0; k < 2; ++k) \
;         acc[ai][bj][m][n] = __builtin_amdgcn_mfma_f32_16x16x32_bf16(Bt[n][k], At[m][k], acc[ai][bj][m][n], 0, 0, 0); __builtin_amdgcn_s_setprio(0); } while (0)
; #define PG8_WAIT_V(n) asm volatile("s_waitcnt vmcnt(" #n ")" ::: "memory")
; #define PG8_WAIT_L(n) asm volatile("s_waitcnt lgkmcnt(" #n ")" ::: "memory")
; #define PG8_BAR __builtin_amdgcn_s_barrier()
; #define PG8_SCHED __builtin_amdgcn_sched_barrier(0)
;     __device__ __forceinline__ void operator()(const f32x4 (&acc)[2][2][4][2], const Unit& u, int wr, int wc, int fr, int fq) const {
;     ...
;         } else if (wc == 0) {
; #pragma unroll
;             for (int ai = 0; ai < 2; ++ai)
; #pragma unroll
;                 for (int m = 0; m < 4; ++m) {
;                     float* rowp = DT + (size_t)(row0 + ai * HALF + m * 16) * 32 + 8 * fq;
;                     *(f32x4*)rowp = acc[ai][0][m][0]; *(f32x4*)(rowp + 4) = acc[ai][0][m][1];
;                 }
; template <class Epi, class Sched, int LD>
; __device__ __forceinline__ void gemm_phase(LAS unsigned char* lds, const Gemm g, const Sched& S, const Epi& E) {
;     ...
;             PG8_BAR; PG8_WAIT_L(0); PG8_MMA(1, 0, At, B0); PG8_BAR; PG8_SCHED;
;             PG8_STAGE(PG8_SB(1, 1), b3 + hstep, voffB);
;             PG8_WAIT_V(6); PG8_BAR; PG8_MMA(1, 1, At, B1); PG8_BAR;
;         }
;         E(acc, cur, wr, wc, fr, fq);
;         if (!has_next) break;
	s_waitcnt lgkmcnt(0)
	s_setprio 0
	v_mfma_f32_16x16x32_bf16 v[64:67], v[148:151], v[180:183], v[64:67]
	v_mfma_f32_16x16x32_bf16 v[60:63], v[156:159], v[180:183], v[60:63]
	v_mfma_f32_16x16x32_bf16 v[56:59], v[148:151], v[188:191], v[56:59]
	v_mfma_f32_16x16x32_bf16 v[52:55], v[156:159], v[188:191], v[52:55]
	v_mfma_f32_16x16x32_bf16 v[40:43], v[148:151], v[196:199], v[40:43]
	v_mfma_f32_16x16x32_bf16 v[36:39], v[156:159], v[196:199], v[36:39]
	v_mfma_f32_16x16x32_bf16 v[24:27], v[148:151], v[204:207], v[24:27]
	v_mfma_f32_16x16x32_bf16 v[20:23], v[156:159], v[204:207], v[20:23]
	v_mfma_f32_16x16x32_bf16 v[64:67], v[152:155], v[184:187], v[64:67]
	v_mfma_f32_16x16x32_bf16 v[60:63], v[176:179], v[184:187], v[60:63]
	v_mfma_f32_16x16x32_bf16 v[56:59], v[152:155], v[192:195], v[56:59]
	v_mfma_f32_16x16x32_bf16 v[52:55], v[176:179], v[192:195], v[52:55]
	v_mfma_f32_16x16x32_bf16 v[40:43], v[152:155], v[200:203], v[40:43]
	v_mfma_f32_16x16x32_bf16 v[36:39], v[176:179], v[200:203], v[36:39]
	s_setprio 3
	s_barrier
	v_mfma_f32_16x16x32_bf16 v[24:27], v[152:155], v[208:211], v[24:27]
	v_mfma_f32_16x16x32_bf16 v[20:23], v[176:179], v[208:211], v[20:23]
	s_setprio 2
	ds_read_b128 v[148:151], v228
	ds_read_b128 v[152:155], v228 offset:1024
	ds_read_b128 v[156:159], v228 offset:2048
	ds_read_b128 v[176:179], v228 offset:3072
	s_add_u32 s4, s56, 0xc000
	s_addc_u32 s5, s57, 0
	s_add_i32 s56, s70, s39
	s_mov_b32 m0, s56
	s_nop 0
	global_load_lds_dwordx4 v132, s[4:5]
	s_add_i32 m0, s56, 0x2000
	s_nop 0
	global_load_lds_dwordx4 v138, s[4:5]
	s_waitcnt vmcnt(6)
	s_barrier
	s_setprio 0
	v_mfma_f32_16x16x32_bf16 v[48:51], v[212:215], v[180:183], v[48:51]
	v_mfma_f32_16x16x32_bf16 v[44:47], v[220:223], v[180:183], v[44:47]
	v_mfma_f32_16x16x32_bf16 v[32:35], v[212:215], v[188:191], v[32:35]
	v_mfma_f32_16x16x32_bf16 v[28:31], v[220:223], v[188:191], v[28:31]
	v_mfma_f32_16x16x32_bf16 v[16:19], v[212:215], v[196:199], v[16:19]
	v_mfma_f32_16x16x32_bf16 v[12:15], v[220:223], v[196:199], v[12:15]
	v_mfma_f32_16x16x32_bf16 v[8:11], v[212:215], v[204:207], v[8:11]
	v_mfma_f32_16x16x32_bf16 v[4:7], v[220:223], v[204:207], v[4:7]
	v_mfma_f32_16x16x32_bf16 v[48:51], v[216:219], v[184:187], v[48:51]
	v_mfma_f32_16x16x32_bf16 v[44:47], v[224:227], v[184:187], v[44:47]
	v_mfma_f32_16x16x32_bf16 v[32:35], v[216:219], v[192:195], v[32:35]
	v_mfma_f32_16x16x32_bf16 v[28:31], v[224:227], v[192:195], v[28:31]
	v_mfma_f32_16x16x32_bf16 v[16:19], v[216:219], v[200:203], v[16:19]
	v_mfma_f32_16x16x32_bf16 v[12:15], v[224:227], v[200:203], v[12:15]
	v_mfma_f32_16x16x32_bf16 v[8:11], v[216:219], v[208:211], v[8:11]
	v_mfma_f32_16x16x32_bf16 v[4:7], v[224:227], v[208:211], v[4:7]
	s_setprio 2
	s_add_i32 s49, s49, 2
	s_add_u32 s54, s54, 0x10000
	s_addc_u32 s55, s55, 0
	s_add_u32 s29, s29, 0x10000
	s_addc_u32 s47, s47, 0
	s_add_u32 s4, s54, 0x4000
	s_addc_u32 s5, s55, 0
	s_cmp_eq_u32 s49, 28
	s_cselect_b32 s4, s50, s4
	s_cselect_b32 s5, s51, s5
	s_cselect_b32 s56, s40, s29
	s_cselect_b32 s57, s41, s47
	s_add_u32 s58, s4, 0x8000
	s_addc_u32 s59, s5, 0
	s_add_i32 s69, 0, 0x10000
	s_cmp_gt_u32 s49, 29
	s_cbranch_scc0 .LBB0_501
	s_barrier
	s_setprio 0
	v_lshl_add_u32 v142, s68, 8, v137
	s_cmp_gt_i32 s67, 35
	s_mov_b64 s[4:5], -1
	s_cbranch_scc0 .LBB0_506
	s_andn2_b64 vcc, exec, s[42:43]
	s_cbranch_vccnz .LBB0_505
	v_or_b32_e32 v150, 16, v142
	v_ashrrev_i32_e32 v143, 31, v142
	v_ashrrev_i32_e32 v151, 31, v150
	v_lshlrev_b64 v[148:149], 7, v[142:143]
	v_lshlrev_b64 v[150:151], 7, v[150:151]
	v_lshl_add_u64 v[148:149], v[140:141], 0, v[148:149]
	v_lshl_add_u64 v[150:151], v[140:141], 0, v[150:151]
	global_store_dwordx4 v[148:149], v[128:131], off
	global_store_dwordx4 v[148:149], v[124:127], off offset:16
	global_store_dwordx4 v[150:151], v[120:123], off
	global_store_dwordx4 v[150:151], v[116:119], off offset:16
	v_or_b32_e32 v150, 32, v142
	v_ashrrev_i32_e32 v151, 31, v150
	v_lshlrev_b64 v[150:151], 7, v[150:151]
	v_lshl_add_u64 v[150:151], v[140:141], 0, v[150:151]
	global_store_dwordx4 v[150:151], v[104:107], off
	global_store_dwordx4 v[150:151], v[100:103], off offset:16
	v_or_b32_e32 v150, 48, v142
	v_ashrrev_i32_e32 v151, 31, v150
	v_lshlrev_b64 v[150:151], 7, v[150:151]
	v_lshl_add_u64 v[150:151], v[140:141], 0, v[150:151]
	s_mov_b64 s[4:5], 0x4000
	global_store_dwordx4 v[150:151], v[88:91], off
	global_store_dwordx4 v[150:151], v[84:87], off offset:16
	v_lshl_add_u64 v[150:151], v[148:149], 0, s[4:5]
	s_movk_i32 s4, 0x4000
	v_add_co_u32_e32 v152, vcc, s4, v148
	s_mov_b64 s[4:5], 0x4800
	s_nop 0
	v_addc_co_u32_e32 v153, vcc, 0, v149, vcc
	global_store_dwordx4 v[152:153], v[64:67], off
	global_store_dwordx4 v[150:151], v[60:63], off offset:16
	v_lshl_add_u64 v[150:151], v[148:149], 0, s[4:5]
	global_store_dwordx4 v[152:153], v[56:59], off offset:2048
	global_store_dwordx4 v[150:151], v[52:55], off offset:16
	s_mov_b64 s[4:5], 0x5000
	v_add_co_u32_e32 v152, vcc, 0x5000, v148
	v_lshl_add_u64 v[150:151], v[148:149], 0, s[4:5]
	s_nop 0
	v_addc_co_u32_e32 v153, vcc, 0, v149, vcc
	s_mov_b64 s[4:5], 0x5800
	global_store_dwordx4 v[152:153], v[40:43], off
	global_store_dwordx4 v[150:151], v[36:39], off offset:16
	v_lshl_add_u64 v[148:149], v[148:149], 0, s[4:5]
	global_store_dwordx4 v[152:153], v[24:27], off offset:2048
	global_store_dwordx4 v[148:149], v[20:23], off offset:16

; #define PG8_STAGE(bufoff, gbase, voff) do { _Pragma("unroll") for (int _i = 0; _i < 2; ++_i) \
;         __builtin_amdgcn_global_load_lds((const unsigned*)((const char*)(gbase) + (voff)[_i]), (LAS unsigned*)(lds + (bufoff) + ldsw + _i * 8192), 16, 0, 0); } while (0)
; #define PG8_LDA(dst, b, h) do { _Pragma("unroll") for (int m = 0; m < 4; ++m) _Pragma("unroll") for (int k = 0; k < 2; ++k) dst[m][k] = *(const LAS bf16x8*)(lds + PG8_SA(b, h) + aoff + m * 2048 + k * 1024); } while (0)
; #define PG8_LDB(dst, b, h) do { _Pragma("unroll") for (int n = 0; n < 2; ++n) _Pragma("unroll") for (int k = 0; k < 2; ++k) dst[n][k] = *(const LAS bf16x8*)(lds + PG8_SB(b, h) + boff + n * 2048 + k * 1024); } while (0)
; #define PG8_SCHED __builtin_amdgcn_sched_barrier(0)
; template <class Epi, class Sched, int LD>
; __device__ __forceinline__ void gemm_phase(LAS unsigned char* lds, const Gemm g, const Sched& S, const Epi& E) {
;     ...
;         const bool has_next = S.next(ui + 1, nxt);
;         const char* nA = has_next ? (const char*)g.A + (size_t)nxt.pm * tstep + (size_t)(nxt.kofs / BK) * kstep : cA; const char* nB = has_next ? (const char*)g.Bt + (size_t)nxt.pn * tstep + (size_t)(nxt.kofs / BK) * kstep : cB;
;         const int nt = cur.nt;
;         for (int t = 0; t < nt; t += 2) {
;             const bool last = (t == nt - 2);
;             const char* a1 = cA + (size_t)(t + 1) * kstep;
;             const char* a2 = last ? nA : cA + (size_t)(t + 2) * kstep; const char* b2 = last ? nB : cB + (size_t)(t + 2) * kstep;
;             const char* a3 = a2 + kstep; const char* b3 = b2 + kstep;
;             PG8_LDB(B0, 0, 0); PG8_SCHED; PG8_LDA(At, 0, 0); PG8_STAGE(PG8_SA(1, 1), a1 + hstep, voffA);
;     ...
;         for (int a = 0; a < 2; ++a)
; #pragma unroll
;             for (int b = 0; b < 2; ++b)
; #pragma unroll
;                 for (int m = 0; m < 4; ++m)
; #pragma unroll
;                     for (int n = 0; n < 2; ++n) acc[a][b][m][n] = (f32x4){0.f, 0.f, 0.f, 0.f};
;         cur = nxt; cA = nA; cB = nB; ++ui;
.LBB0_774:
	s_add_i32 s68, s65, -2
	s_add_u32 s46, s46, 0xc000
	s_addc_u32 s47, s47, 0
	s_add_u32 s69, s48, 0x10000
	v_mov_b32_e32 v4, 0
	s_addc_u32 s70, s49, 0
	s_mov_b32 s4, 0
	v_mov_b32_e32 v5, v4
	v_mov_b32_e32 v6, v4
	v_mov_b32_e32 v7, v4
	v_mov_b32_e32 v8, v4
	v_mov_b32_e32 v9, v4
	v_mov_b32_e32 v10, v4
	v_mov_b32_e32 v11, v4
	v_mov_b32_e32 v20, v4
	v_mov_b32_e32 v21, v4
	v_mov_b32_e32 v22, v4
	v_mov_b32_e32 v23, v4
	v_mov_b32_e32 v24, v4
	v_mov_b32_e32 v25, v4
	v_mov_b32_e32 v26, v4
	v_mov_b32_e32 v27, v4
	v_mov_b32_e32 v36, v4
	v_mov_b32_e32 v37, v4
	v_mov_b32_e32 v38, v4
	v_mov_b32_e32 v39, v4
	v_mov_b32_e32 v40, v4
	v_mov_b32_e32 v41, v4
	v_mov_b32_e32 v42, v4
	v_mov_b32_e32 v43, v4
	v_mov_b32_e32 v52, v4
	v_mov_b32_e32 v53, v4
	v_mov_b32_e32 v54, v4
	v_mov_b32_e32 v55, v4
	v_mov_b32_e32 v56, v4
	v_mov_b32_e32 v57, v4
	v_mov_b32_e32 v58, v4
	v_mov_b32_e32 v59, v4
	v_mov_b32_e32 v12, v4
	v_mov_b32_e32 v13, v4
	v_mov_b32_e32 v14, v4
	v_mov_b32_e32 v15, v4
	v_mov_b32_e32 v16, v4
	v_mov_b32_e32 v17, v4
	v_mov_b32_e32 v18, v4
	v_mov_b32_e32 v19, v4
	v_mov_b32_e32 v28, v4
	v_mov_b32_e32 v29, v4
	v_mov_b32_e32 v30, v4
	v_mov_b32_e32 v31, v4
	v_mov_b32_e32 v32, v4
	v_mov_b32_e32 v33, v4
	v_mov_b32_e32 v34, v4
	v_mov_b32_e32 v35, v4
	v_mov_b32_e32 v44, v4
	v_mov_b32_e32 v45, v4
	v_mov_b32_e32 v46, v4
	v_mov_b32_e32 v47, v4
	v_mov_b32_e32 v48, v4
	v_mov_b32_e32 v49, v4
	v_mov_b32_e32 v50, v4
	v_mov_b32_e32 v51, v4
	v_mov_b32_e32 v60, v4
	v_mov_b32_e32 v61, v4
	v_mov_b32_e32 v62, v4
	v_mov_b32_e32 v63, v4
	v_mov_b32_e32 v64, v4
	v_mov_b32_e32 v65, v4
	v_mov_b32_e32 v66, v4
	v_mov_b32_e32 v67, v4
	v_mov_b32_e32 v68, v4
	v_mov_b32_e32 v69, v4
	v_mov_b32_e32 v70, v4
	v_mov_b32_e32 v71, v4
	v_mov_b32_e32 v72, v4
	v_mov_b32_e32 v73, v4
	v_mov_b32_e32 v74, v4
	v_mov_b32_e32 v75, v4
	v_mov_b32_e32 v84, v4
	v_mov_b32_e32 v85, v4
	v_mov_b32_e32 v86, v4
	v_mov_b32_e32 v87, v4
	v_mov_b32_e32 v88, v4
	v_mov_b32_e32 v89, v4
	v_mov_b32_e32 v90, v4
	v_mov_b32_e32 v91, v4
	v_mov_b32_e32 v100, v4
	v_mov_b32_e32 v101, v4
	v_mov_b32_e32 v102, v4
	v_mov_b32_e32 v103, v4
	v_mov_b32_e32 v104, v4
	v_mov_b32_e32 v105, v4
	v_mov_b32_e32 v106, v4
	v_mov_b32_e32 v107, v4
	v_mov_b32_e32 v116, v4
	v_mov_b32_e32 v117, v4
	v_mov_b32_e32 v118, v4
	v_mov_b32_e32 v119, v4
	v_mov_b32_e32 v120, v4
	v_mov_b32_e32 v121, v4
	v_mov_b32_e32 v122, v4
	v_mov_b32_e32 v123, v4
	v_mov_b32_e32 v76, v4
	v_mov_b32_e32 v77, v4
	v_mov_b32_e32 v78, v4
	v_mov_b32_e32 v79, v4
	v_mov_b32_e32 v80, v4
	v_mov_b32_e32 v81, v4
	v_mov_b32_e32 v82, v4
	v_mov_b32_e32 v83, v4
	v_mov_b32_e32 v92, v4
	v_mov_b32_e32 v93, v4
	v_mov_b32_e32 v94, v4
	v_mov_b32_e32 v95, v4
	v_mov_b32_e32 v96, v4
	v_mov_b32_e32 v97, v4
	v_mov_b32_e32 v98, v4
	v_mov_b32_e32 v99, v4
	v_mov_b32_e32 v108, v4
	v_mov_b32_e32 v109, v4
	v_mov_b32_e32 v110, v4
	v_mov_b32_e32 v111, v4
	v_mov_b32_e32 v112, v4
	v_mov_b32_e32 v113, v4
	v_mov_b32_e32 v114, v4
	v_mov_b32_e32 v115, v4
	v_mov_b32_e32 v124, v4
	v_mov_b32_e32 v125, v4
	v_mov_b32_e32 v126, v4
	v_mov_b32_e32 v127, v4
	v_mov_b32_e32 v128, v4
	v_mov_b32_e32 v129, v4
	v_mov_b32_e32 v130, v4
	v_mov_b32_e32 v131, v4
	ds_read_b128 v[140:143], v228
	ds_read_b128 v[150:153], v228 offset:1024
	ds_read_b128 v[154:157], v228 offset:2048
	ds_read_b128 v[176:179], v228 offset:3072
	s_add_i32 s71, s4, 2
	s_add_u32 s48, s46, 0x4000
	s_addc_u32 s5, s47, 0
	s_cmp_eq_u32 s68, s4
	s_cselect_b32 s4, s42, s48
	s_cselect_b32 s5, s43, s5
	s_cselect_b32 s48, s44, s69
	s_cselect_b32 s49, s45, s70
	s_add_u32 s50, s4, 0x8000
	s_addc_u32 s51, s5, 0
	s_add_i32 s72, 0, 0x10000
	s_branch .Lrot_down_body

; #define PG8_STAGE(bufoff, gbase, voff) do { _Pragma("unroll") for (int _i = 0; _i < 2; ++_i) \
;         __builtin_amdgcn_global_load_lds((const unsigned*)((const char*)(gbase) + (voff)[_i]), (LAS unsigned*)(lds + (bufoff) + ldsw + _i * 8192), 16, 0, 0); } while (0)
; #define PG8_LDA(dst, b, h) do { _Pragma("unroll") for (int m = 0; m < 4; ++m) _Pragma("unroll") for (int k = 0; k < 2; ++k) dst[m][k] = *(const LAS bf16x8*)(lds + PG8_SA(b, h) + aoff + m * 2048 + k * 1024); } while (0)
; #define PG8_LDB(dst, b, h) do { _Pragma("unroll") for (int n = 0; n < 2; ++n) _Pragma("unroll") for (int k = 0; k < 2; ++k) dst[n][k] = *(const LAS bf16x8*)(lds + PG8_SB(b, h) + boff + n * 2048 + k * 1024); } while (0)
; #define PG8_SCHED __builtin_amdgcn_sched_barrier(0)
; template <class Epi, class Sched, int LD>
; __device__ __forceinline__ void gemm_phase(LAS unsigned char* lds, const Gemm g, const Sched& S, const Epi& E) {
;     ...
;         const bool has_next = S.next(ui + 1, nxt);
;         const char* nA = has_next ? (const char*)g.A + (size_t)nxt.pm * tstep + (size_t)(nxt.kofs / BK) * kstep : cA; const char* nB = has_next ? (const char*)g.Bt + (size_t)nxt.pn * tstep + (size_t)(nxt.kofs / BK) * kstep : cB;
;         const int nt = cur.nt;
;         for (int t = 0; t < nt; t += 2) {
;             const bool last = (t == nt - 2);
;             const char* a1 = cA + (size_t)(t + 1) * kstep;
;             const char* a2 = last ? nA : cA + (size_t)(t + 2) * kstep; const char* b2 = last ? nB : cB + (size_t)(t + 2) * kstep;
;             const char* a3 = a2 + kstep; const char* b3 = b2 + kstep;
;             PG8_LDB(B0, 0, 0); PG8_SCHED; PG8_LDA(At, 0, 0); PG8_STAGE(PG8_SA(1, 1), a1 + hstep, voffA);
;     ...
;         for (int a = 0; a < 2; ++a)
; #pragma unroll
;             for (int b = 0; b < 2; ++b)
; #pragma unroll
;                 for (int m = 0; m < 4; ++m)
; #pragma unroll
;                     for (int n = 0; n < 2; ++n) acc[a][b][m][n] = (f32x4){0.f, 0.f, 0.f, 0.f};
;         cur = nxt; cA = nA; cB = nB; ++ui;
.LBB0_898:
	s_add_u32 s50, s4, 0xc000
	s_addc_u32 s51, s5, 0
	s_add_u32 s45, s54, 0x10000
	v_mov_b32_e32 v4, 0
	s_addc_u32 s47, s55, 0
	s_mov_b32 s70, -2
	v_mov_b32_e32 v5, v4
	v_mov_b32_e32 v6, v4
	v_mov_b32_e32 v7, v4
	v_mov_b32_e32 v12, v4
	v_mov_b32_e32 v13, v4
	v_mov_b32_e32 v14, v4
	v_mov_b32_e32 v15, v4
	v_mov_b32_e32 v20, v4
	v_mov_b32_e32 v21, v4
	v_mov_b32_e32 v22, v4
	v_mov_b32_e32 v23, v4
	v_mov_b32_e32 v28, v4
	v_mov_b32_e32 v29, v4
	v_mov_b32_e32 v30, v4
	v_mov_b32_e32 v31, v4
	v_mov_b32_e32 v36, v4
	v_mov_b32_e32 v37, v4
	v_mov_b32_e32 v38, v4
	v_mov_b32_e32 v39, v4
	v_mov_b32_e32 v44, v4
	v_mov_b32_e32 v45, v4
	v_mov_b32_e32 v46, v4
	v_mov_b32_e32 v47, v4
	v_mov_b32_e32 v52, v4
	v_mov_b32_e32 v53, v4
	v_mov_b32_e32 v54, v4
	v_mov_b32_e32 v55, v4
	v_mov_b32_e32 v60, v4
	v_mov_b32_e32 v61, v4
	v_mov_b32_e32 v62, v4
	v_mov_b32_e32 v63, v4
	v_mov_b32_e32 v8, v4
	v_mov_b32_e32 v9, v4
	v_mov_b32_e32 v10, v4
	v_mov_b32_e32 v11, v4
	v_mov_b32_e32 v16, v4
	v_mov_b32_e32 v17, v4
	v_mov_b32_e32 v18, v4
	v_mov_b32_e32 v19, v4
	v_mov_b32_e32 v24, v4
	v_mov_b32_e32 v25, v4
	v_mov_b32_e32 v26, v4
	v_mov_b32_e32 v27, v4
	v_mov_b32_e32 v32, v4
	v_mov_b32_e32 v33, v4
	v_mov_b32_e32 v34, v4
	v_mov_b32_e32 v35, v4
	v_mov_b32_e32 v40, v4
	v_mov_b32_e32 v41, v4
	v_mov_b32_e32 v42, v4
	v_mov_b32_e32 v43, v4
	v_mov_b32_e32 v48, v4
	v_mov_b32_e32 v49, v4
	v_mov_b32_e32 v50, v4
	v_mov_b32_e32 v51, v4
	v_mov_b32_e32 v56, v4
	v_mov_b32_e32 v57, v4
	v_mov_b32_e32 v58, v4
	v_mov_b32_e32 v59, v4
	v_mov_b32_e32 v64, v4
	v_mov_b32_e32 v65, v4
	v_mov_b32_e32 v66, v4
	v_mov_b32_e32 v67, v4
	v_mov_b32_e32 v68, v4
	v_mov_b32_e32 v69, v4
	v_mov_b32_e32 v70, v4
	v_mov_b32_e32 v71, v4
	v_mov_b32_e32 v76, v4
	v_mov_b32_e32 v77, v4
	v_mov_b32_e32 v78, v4
	v_mov_b32_e32 v79, v4
	v_mov_b32_e32 v84, v4
	v_mov_b32_e32 v85, v4
	v_mov_b32_e32 v86, v4
	v_mov_b32_e32 v87, v4
	v_mov_b32_e32 v92, v4
	v_mov_b32_e32 v93, v4
	v_mov_b32_e32 v94, v4
	v_mov_b32_e32 v95, v4
	v_mov_b32_e32 v100, v4
	v_mov_b32_e32 v101, v4
	v_mov_b32_e32 v102, v4
	v_mov_b32_e32 v103, v4
	v_mov_b32_e32 v108, v4
	v_mov_b32_e32 v109, v4
	v_mov_b32_e32 v110, v4
	v_mov_b32_e32 v111, v4
	v_mov_b32_e32 v116, v4
	v_mov_b32_e32 v117, v4
	v_mov_b32_e32 v118, v4
	v_mov_b32_e32 v119, v4
	v_mov_b32_e32 v124, v4
	v_mov_b32_e32 v125, v4
	v_mov_b32_e32 v126, v4
	v_mov_b32_e32 v127, v4
	v_mov_b32_e32 v72, v4
	v_mov_b32_e32 v73, v4
	v_mov_b32_e32 v74, v4
	v_mov_b32_e32 v75, v4
	v_mov_b32_e32 v80, v4
	v_mov_b32_e32 v81, v4
	v_mov_b32_e32 v82, v4
	v_mov_b32_e32 v83, v4
	v_mov_b32_e32 v88, v4
	v_mov_b32_e32 v89, v4
	v_mov_b32_e32 v90, v4
	v_mov_b32_e32 v91, v4
	v_mov_b32_e32 v96, v4
	v_mov_b32_e32 v97, v4
	v_mov_b32_e32 v98, v4
	v_mov_b32_e32 v99, v4
	v_mov_b32_e32 v104, v4
	v_mov_b32_e32 v105, v4
	v_mov_b32_e32 v106, v4
	v_mov_b32_e32 v107, v4
	v_mov_b32_e32 v112, v4
	v_mov_b32_e32 v113, v4
	v_mov_b32_e32 v114, v4
	v_mov_b32_e32 v115, v4
	v_mov_b32_e32 v120, v4
	v_mov_b32_e32 v121, v4
	v_mov_b32_e32 v122, v4
	v_mov_b32_e32 v123, v4
	v_mov_b32_e32 v128, v4
	v_mov_b32_e32 v129, v4
	v_mov_b32_e32 v130, v4
	v_mov_b32_e32 v131, v4
	ds_read_b128 v[146:149], v228
	ds_read_b128 v[150:153], v228 offset:1024
	ds_read_b128 v[154:157], v228 offset:2048
	ds_read_b128 v[176:179], v228 offset:3072
	s_add_u32 s4, s50, 0x4000
	s_addc_u32 s5, s51, 0
	s_cmp_eq_u32 s70, 28
	s_cselect_b32 s4, s48, s4
	s_cselect_b32 s5, s49, s5
	s_cselect_b32 s54, s40, s45
	s_cselect_b32 s55, s41, s47
	s_add_u32 s56, s4, 0x8000
	s_addc_u32 s57, s5, 0
	s_add_i32 s71, 0, 0x10000
	s_branch .Lrot_gu_body

; #define PG8_STAGE(bufoff, gbase, voff) do { _Pragma("unroll") for (int _i = 0; _i < 2; ++_i) \
;         __builtin_amdgcn_global_load_lds((const unsigned*)((const char*)(gbase) + (voff)[_i]), (LAS unsigned*)(lds + (bufoff) + ldsw + _i * 8192), 16, 0, 0); } while (0)
; #define PG8_LDA(dst, b, h) do { _Pragma("unroll") for (int m = 0; m < 4; ++m) _Pragma("unroll") for (int k = 0; k < 2; ++k) dst[m][k] = *(const LAS bf16x8*)(lds + PG8_SA(b, h) + aoff + m * 2048 + k * 1024); } while (0)
; #define PG8_LDB(dst, b, h) do { _Pragma("unroll") for (int n = 0; n < 2; ++n) _Pragma("unroll") for (int k = 0; k < 2; ++k) dst[n][k] = *(const LAS bf16x8*)(lds + PG8_SB(b, h) + boff + n * 2048 + k * 1024); } while (0)
; #define PG8_MMA(ai, bj, At, Bt) do { __builtin_amdgcn_s_setprio(1); _Pragma("unroll") for (int m = 0; m < 4; ++m) _Pragma("unroll") for (int n = 0; n < 2; ++n) _Pragma("unroll") for (int k = 0; k < 2; ++k) \
;         acc[ai][bj][m][n] = __builtin_amdgcn_mfma_f32_16x16x32_bf16(Bt[n][k], At[m][k], acc[ai][bj][m][n], 0, 0, 0); __builtin_amdgcn_s_setprio(0); } while (0)
; #define PG8_WAIT_V(n) asm volatile("s_waitcnt vmcnt(" #n ")" ::: "memory")
; #define PG8_WAIT_L(n) asm volatile("s_waitcnt lgkmcnt(" #n ")" ::: "memory")
; #define PG8_BAR __builtin_amdgcn_s_barrier()
; #define PG8_SCHED __builtin_amdgcn_sched_barrier(0)
; template <class Epi, class Sched, int LD>
; __device__ __forceinline__ void gemm_phase(LAS unsigned char* lds, const Gemm g, const Sched& S, const Epi& E) {
;     ...
;             PG8_LDB(B0, 0, 0); PG8_SCHED; PG8_LDA(At, 0, 0); PG8_STAGE(PG8_SA(1, 1), a1 + hstep, voffA);
;             PG8_WAIT_L(8); PG8_BAR; PG8_WAIT_L(0); PG8_MMA(0, 0, At, B0); PG8_BAR; PG8_SCHED;
;             PG8_LDB(B1, 0, 1); PG8_STAGE(PG8_SB(0, 0), b2, voffB);
;             PG8_BAR; PG8_WAIT_L(0); PG8_MMA(0, 1, At, B1); PG8_BAR;
;             PG8_LDA(At, 0, 1); PG8_STAGE(PG8_SA(0, 0), a2, voffA);
;             PG8_BAR; PG8_WAIT_L(0); PG8_MMA(1, 0, At, B0); PG8_BAR; PG8_SCHED;
;             PG8_STAGE(PG8_SB(0, 1), b2 + hstep, voffB);
;             PG8_WAIT_V(6); PG8_BAR; PG8_MMA(1, 1, At, B1); PG8_BAR;
;             PG8_LDB(B0, 1, 0); PG8_SCHED; PG8_LDA(At, 1, 0); PG8_STAGE(PG8_SA(0, 1), a2 + hstep, voffA);
.Lrot_gu_body:
	s_add_i32 m0, s29, 0xc000
	ds_read_b128 v[180:183], v144
	ds_read_b128 v[184:187], v144 offset:1024
	ds_read_b128 v[188:191], v144 offset:2048
	ds_read_b128 v[192:195], v144 offset:3072
	ds_read_b128 v[196:199], v144 offset:4096
	ds_read_b128 v[200:203], v144 offset:5120
	ds_read_b128 v[204:207], v144 offset:6144
	ds_read_b128 v[208:211], v144 offset:7168
	global_load_lds_dwordx4 v138, s[50:51]
	s_add_i32 m0, s29, 0xe000
	s_nop 0
	global_load_lds_dwordx4 v140, s[50:51]
	s_waitcnt lgkmcnt(8)
	s_barrier
	s_waitcnt lgkmcnt(0)
	s_setprio 0
	v_mfma_f32_16x16x32_bf16 v[128:131], v[146:149], v[180:183], v[128:131]
	v_mfma_f32_16x16x32_bf16 v[120:123], v[154:157], v[180:183], v[120:123]
	v_mfma_f32_16x16x32_bf16 v[112:115], v[146:149], v[188:191], v[112:115]
	v_mfma_f32_16x16x32_bf16 v[104:107], v[154:157], v[188:191], v[104:107]
	v_mfma_f32_16x16x32_bf16 v[96:99], v[146:149], v[196:199], v[96:99]
	v_mfma_f32_16x16x32_bf16 v[88:91], v[154:157], v[196:199], v[88:91]
	v_mfma_f32_16x16x32_bf16 v[80:83], v[146:149], v[204:207], v[80:83]
	v_mfma_f32_16x16x32_bf16 v[72:75], v[154:157], v[204:207], v[72:75]
	v_mfma_f32_16x16x32_bf16 v[128:131], v[150:153], v[184:187], v[128:131]
	v_mfma_f32_16x16x32_bf16 v[120:123], v[176:179], v[184:187], v[120:123]
	v_mfma_f32_16x16x32_bf16 v[112:115], v[150:153], v[192:195], v[112:115]
	v_mfma_f32_16x16x32_bf16 v[104:107], v[176:179], v[192:195], v[104:107]
	v_mfma_f32_16x16x32_bf16 v[96:99], v[150:153], v[200:203], v[96:99]
	v_mfma_f32_16x16x32_bf16 v[88:91], v[176:179], v[200:203], v[88:91]
	s_setprio 3
	s_barrier
	v_mfma_f32_16x16x32_bf16 v[80:83], v[150:153], v[208:211], v[80:83]
	v_mfma_f32_16x16x32_bf16 v[72:75], v[176:179], v[208:211], v[72:75]
	s_setprio 2
	s_add_i32 s74, 0, 0x14000
	s_add_i32 s71, s71, s28
	s_mov_b32 m0, s71
	ds_read_b128 v[212:215], v228 offset:16384
	ds_read_b128 v[216:219], v228 offset:17408
	ds_read_b128 v[220:223], v228 offset:18432
	ds_read_b128 v[224:227], v228 offset:19456
	global_load_lds_dwordx4 v138, s[54:55]
	s_add_i32 m0, s71, 0x2000
	s_nop 0
	global_load_lds_dwordx4 v140, s[54:55]
	s_barrier
	s_waitcnt lgkmcnt(0)
	s_setprio 0
	v_mfma_f32_16x16x32_bf16 v[124:127], v[212:215], v[180:183], v[124:127]
	v_mfma_f32_16x16x32_bf16 v[116:119], v[220:223], v[180:183], v[116:119]
	v_mfma_f32_16x16x32_bf16 v[108:111], v[212:215], v[188:191], v[108:111]
	v_mfma_f32_16x16x32_bf16 v[100:103], v[220:223], v[188:191], v[100:103]
	v_mfma_f32_16x16x32_bf16 v[92:95], v[212:215], v[196:199], v[92:95]
	v_mfma_f32_16x16x32_bf16 v[84:87], v[220:223], v[196:199], v[84:87]
	v_mfma_f32_16x16x32_bf16 v[76:79], v[212:215], v[204:207], v[76:79]
	v_mfma_f32_16x16x32_bf16 v[68:71], v[220:223], v[204:207], v[68:71]
	v_mfma_f32_16x16x32_bf16 v[124:127], v[216:219], v[184:187], v[124:127]
	v_mfma_f32_16x16x32_bf16 v[116:119], v[224:227], v[184:187], v[116:119]
	v_mfma_f32_16x16x32_bf16 v[108:111], v[216:219], v[192:195], v[108:111]
	v_mfma_f32_16x16x32_bf16 v[100:103], v[224:227], v[192:195], v[100:103]
	v_mfma_f32_16x16x32_bf16 v[92:95], v[216:219], v[200:203], v[92:95]
	v_mfma_f32_16x16x32_bf16 v[84:87], v[224:227], v[200:203], v[84:87]
	v_mfma_f32_16x16x32_bf16 v[76:79], v[216:219], v[208:211], v[76:79]
	v_mfma_f32_16x16x32_bf16 v[68:71], v[224:227], v[208:211], v[68:71]
	s_setprio 2
	s_mov_b32 m0, s29
	s_barrier
	ds_read_b128 v[180:183], v144 offset:16384
	ds_read_b128 v[184:187], v144 offset:17408
	ds_read_b128 v[188:191], v144 offset:18432
	ds_read_b128 v[192:195], v144 offset:19456
	ds_read_b128 v[196:199], v144 offset:20480
	ds_read_b128 v[200:203], v144 offset:21504
	ds_read_b128 v[204:207], v144 offset:22528
	ds_read_b128 v[208:211], v144 offset:23552
	global_load_lds_dwordx4 v138, s[4:5]
	s_mov_b32 m0, s39
	s_nop 0
	global_load_lds_dwordx4 v140, s[4:5]
	s_waitcnt vmcnt(10)
	s_barrier
	s_waitcnt lgkmcnt(0)
	s_setprio 0
	v_mfma_f32_16x16x32_bf16 v[64:67], v[146:149], v[180:183], v[64:67]
	v_mfma_f32_16x16x32_bf16 v[56:59], v[154:157], v[180:183], v[56:59]
	v_mfma_f32_16x16x32_bf16 v[48:51], v[146:149], v[188:191], v[48:51]
	v_mfma_f32_16x16x32_bf16 v[40:43], v[154:157], v[188:191], v[40:43]
	v_mfma_f32_16x16x32_bf16 v[32:35], v[146:149], v[196:199], v[32:35]
	v_mfma_f32_16x16x32_bf16 v[24:27], v[154:157], v[196:199], v[24:27]
	v_mfma_f32_16x16x32_bf16 v[16:19], v[146:149], v[204:207], v[16:19]
	v_mfma_f32_16x16x32_bf16 v[8:11], v[154:157], v[204:207], v[8:11]
	v_mfma_f32_16x16x32_bf16 v[64:67], v[150:153], v[184:187], v[64:67]
	v_mfma_f32_16x16x32_bf16 v[56:59], v[176:179], v[184:187], v[56:59]
	v_mfma_f32_16x16x32_bf16 v[48:51], v[150:153], v[192:195], v[48:51]
	v_mfma_f32_16x16x32_bf16 v[40:43], v[176:179], v[192:195], v[40:43]
	v_mfma_f32_16x16x32_bf16 v[32:35], v[150:153], v[200:203], v[32:35]
	v_mfma_f32_16x16x32_bf16 v[24:27], v[176:179], v[200:203], v[24:27]
	s_setprio 3
	s_barrier
	v_mfma_f32_16x16x32_bf16 v[16:19], v[150:153], v[208:211], v[16:19]
	v_mfma_f32_16x16x32_bf16 v[8:11], v[176:179], v[208:211], v[8:11]
	s_setprio 2
	ds_read_b128 v[146:149], v228 offset:32768
	ds_read_b128 v[150:153], v228 offset:33792
	ds_read_b128 v[154:157], v228 offset:34816
	ds_read_b128 v[176:179], v228 offset:35840
	s_add_u32 s72, s54, 0x4000
	s_addc_u32 s73, s55, 0
	s_add_i32 s71, s74, s28
	s_mov_b32 m0, s71
	s_nop 0
	global_load_lds_dwordx4 v138, s[72:73]
	s_add_i32 m0, s71, 0x2000
	s_nop 0
	global_load_lds_dwordx4 v140, s[72:73]
	s_waitcnt vmcnt(6)
	s_barrier
; #define PG8_STAGE(bufoff, gbase, voff) do { _Pragma("unroll") for (int _i = 0; _i < 2; ++_i) \
;         __builtin_amdgcn_global_load_lds((const unsigned*)((const char*)(gbase) + (voff)[_i]), (LAS unsigned*)(lds + (bufoff) + ldsw + _i * 8192), 16, 0, 0); } while (0)
; #define PG8_LDA(dst, b, h) do { _Pragma("unroll") for (int m = 0; m < 4; ++m) _Pragma("unroll") for (int k = 0; k < 2; ++k) dst[m][k] = *(const LAS bf16x8*)(lds + PG8_SA(b, h) + aoff + m * 2048 + k * 1024); } while (0)
; #define PG8_LDB(dst, b, h) do { _Pragma("unroll") for (int n = 0; n < 2; ++n) _Pragma("unroll") for (int k = 0; k < 2; ++k) dst[n][k] = *(const LAS bf16x8*)(lds + PG8_SB(b, h) + boff + n * 2048 + k * 1024); } while (0)
; #define PG8_MMA(ai, bj, At, Bt) do { __builtin_amdgcn_s_setprio(1); _Pragma("unroll") for (int m = 0; m < 4; ++m) _Pragma("unroll") for (int n = 0; n < 2; ++n) _Pragma("unroll") for (int k = 0; k < 2; ++k) \
;         acc[ai][bj][m][n] = __builtin_amdgcn_mfma_f32_16x16x32_bf16(Bt[n][k], At[m][k], acc[ai][bj][m][n], 0, 0, 0); __builtin_amdgcn_s_setprio(0); } while (0)
; #define PG8_WAIT_V(n) asm volatile("s_waitcnt vmcnt(" #n ")" ::: "memory")
; #define PG8_WAIT_L(n) asm volatile("s_waitcnt lgkmcnt(" #n ")" ::: "memory")
; #define PG8_BAR __builtin_amdgcn_s_barrier()
; #define PG8_SCHED __builtin_amdgcn_sched_barrier(0)
; template <class Epi, class Sched, int LD>
; __device__ __forceinline__ void gemm_phase(LAS unsigned char* lds, const Gemm g, const Sched& S, const Epi& E) {
;     ...
;             PG8_WAIT_V(6); PG8_BAR; PG8_MMA(1, 1, At, B1); PG8_BAR;
;             PG8_LDB(B0, 1, 0); PG8_SCHED; PG8_LDA(At, 1, 0); PG8_STAGE(PG8_SA(0, 1), a2 + hstep, voffA);
;             PG8_WAIT_L(8); PG8_BAR; PG8_WAIT_L(0); PG8_MMA(0, 0, At, B0); PG8_BAR; PG8_SCHED;
;             PG8_LDB(B1, 1, 1); PG8_STAGE(PG8_SB(1, 0), b3, voffB);
;             PG8_BAR; PG8_WAIT_L(0); PG8_MMA(0, 1, At, B1); PG8_BAR;
;             PG8_LDA(At, 1, 1); PG8_STAGE(PG8_SA(1, 0), a3, voffA);
;             PG8_BAR; PG8_WAIT_L(0); PG8_MMA(1, 0, At, B0); PG8_BAR; PG8_SCHED;
	s_setprio 0
	v_mfma_f32_16x16x32_bf16 v[60:63], v[212:215], v[180:183], v[60:63]
	v_mfma_f32_16x16x32_bf16 v[52:55], v[220:223], v[180:183], v[52:55]
	v_mfma_f32_16x16x32_bf16 v[44:47], v[212:215], v[188:191], v[44:47]
	v_mfma_f32_16x16x32_bf16 v[36:39], v[220:223], v[188:191], v[36:39]
	v_mfma_f32_16x16x32_bf16 v[28:31], v[212:215], v[196:199], v[28:31]
	v_mfma_f32_16x16x32_bf16 v[20:23], v[220:223], v[196:199], v[20:23]
	v_mfma_f32_16x16x32_bf16 v[12:15], v[212:215], v[204:207], v[12:15]
	v_mfma_f32_16x16x32_bf16 v[4:7], v[220:223], v[204:207], v[4:7]
	v_mfma_f32_16x16x32_bf16 v[60:63], v[216:219], v[184:187], v[60:63]
	v_mfma_f32_16x16x32_bf16 v[52:55], v[224:227], v[184:187], v[52:55]
	v_mfma_f32_16x16x32_bf16 v[44:47], v[216:219], v[192:195], v[44:47]
	v_mfma_f32_16x16x32_bf16 v[36:39], v[224:227], v[192:195], v[36:39]
	v_mfma_f32_16x16x32_bf16 v[28:31], v[216:219], v[200:203], v[28:31]
	v_mfma_f32_16x16x32_bf16 v[20:23], v[224:227], v[200:203], v[20:23]
	v_mfma_f32_16x16x32_bf16 v[12:15], v[216:219], v[208:211], v[12:15]
	v_mfma_f32_16x16x32_bf16 v[4:7], v[224:227], v[208:211], v[4:7]
	s_setprio 2
	s_add_i32 s71, 0, 0x18000
	s_barrier
	s_add_u32 s4, s4, 0x4000
	s_addc_u32 s5, s5, 0
	s_mov_b32 m0, s52
	ds_read_b128 v[180:183], v144 offset:32768
	ds_read_b128 v[184:187], v144 offset:33792
	ds_read_b128 v[188:191], v144 offset:34816
	ds_read_b128 v[192:195], v144 offset:35840
	ds_read_b128 v[196:199], v144 offset:36864
	ds_read_b128 v[200:203], v144 offset:37888
	ds_read_b128 v[204:207], v144 offset:38912
	ds_read_b128 v[208:211], v144 offset:39936
	global_load_lds_dwordx4 v138, s[4:5]
	s_mov_b32 m0, s53
	s_nop 0
	global_load_lds_dwordx4 v140, s[4:5]
	s_waitcnt lgkmcnt(8)
	s_barrier
	s_waitcnt lgkmcnt(0)
	s_setprio 0
	v_mfma_f32_16x16x32_bf16 v[128:131], v[146:149], v[180:183], v[128:131]
	v_mfma_f32_16x16x32_bf16 v[120:123], v[154:157], v[180:183], v[120:123]
	v_mfma_f32_16x16x32_bf16 v[112:115], v[146:149], v[188:191], v[112:115]
	v_mfma_f32_16x16x32_bf16 v[104:107], v[154:157], v[188:191], v[104:107]
	v_mfma_f32_16x16x32_bf16 v[96:99], v[146:149], v[196:199], v[96:99]
	v_mfma_f32_16x16x32_bf16 v[88:91], v[154:157], v[196:199], v[88:91]
	v_mfma_f32_16x16x32_bf16 v[80:83], v[146:149], v[204:207], v[80:83]
	v_mfma_f32_16x16x32_bf16 v[72:75], v[154:157], v[204:207], v[72:75]
	v_mfma_f32_16x16x32_bf16 v[128:131], v[150:153], v[184:187], v[128:131]
	v_mfma_f32_16x16x32_bf16 v[120:123], v[176:179], v[184:187], v[120:123]
	v_mfma_f32_16x16x32_bf16 v[112:115], v[150:153], v[192:195], v[112:115]
	v_mfma_f32_16x16x32_bf16 v[104:107], v[176:179], v[192:195], v[104:107]
	v_mfma_f32_16x16x32_bf16 v[96:99], v[150:153], v[200:203], v[96:99]
	v_mfma_f32_16x16x32_bf16 v[88:91], v[176:179], v[200:203], v[88:91]
	s_setprio 3
	s_barrier
	v_mfma_f32_16x16x32_bf16 v[80:83], v[150:153], v[208:211], v[80:83]
	v_mfma_f32_16x16x32_bf16 v[72:75], v[176:179], v[208:211], v[72:75]
	s_setprio 2
	s_add_i32 s72, 0, 0x1c000
	s_add_u32 s4, s54, 0x8000
	s_addc_u32 s5, s55, 0
	s_add_i32 s71, s71, s28
	s_mov_b32 m0, s71
	ds_read_b128 v[212:215], v228 offset:49152
	ds_read_b128 v[216:219], v228 offset:50176
	ds_read_b128 v[220:223], v228 offset:51200
	ds_read_b128 v[224:227], v228 offset:52224
	global_load_lds_dwordx4 v138, s[4:5]
	s_add_i32 m0, s71, 0x2000
	s_nop 0
	global_load_lds_dwordx4 v140, s[4:5]
	s_barrier
	s_waitcnt lgkmcnt(0)
	s_setprio 0
	v_mfma_f32_16x16x32_bf16 v[124:127], v[212:215], v[180:183], v[124:127]
	v_mfma_f32_16x16x32_bf16 v[116:119], v[220:223], v[180:183], v[116:119]
	v_mfma_f32_16x16x32_bf16 v[108:111], v[212:215], v[188:191], v[108:111]
	v_mfma_f32_16x16x32_bf16 v[100:103], v[220:223], v[188:191], v[100:103]
	v_mfma_f32_16x16x32_bf16 v[92:95], v[212:215], v[196:199], v[92:95]
	v_mfma_f32_16x16x32_bf16 v[84:87], v[220:223], v[196:199], v[84:87]
	v_mfma_f32_16x16x32_bf16 v[76:79], v[212:215], v[204:207], v[76:79]
	v_mfma_f32_16x16x32_bf16 v[68:71], v[220:223], v[204:207], v[68:71]
	v_mfma_f32_16x16x32_bf16 v[124:127], v[216:219], v[184:187], v[124:127]
	v_mfma_f32_16x16x32_bf16 v[116:119], v[224:227], v[184:187], v[116:119]
	v_mfma_f32_16x16x32_bf16 v[108:111], v[216:219], v[192:195], v[108:111]
	v_mfma_f32_16x16x32_bf16 v[100:103], v[224:227], v[192:195], v[100:103]
	v_mfma_f32_16x16x32_bf16 v[92:95], v[216:219], v[200:203], v[92:95]
	v_mfma_f32_16x16x32_bf16 v[84:87], v[224:227], v[200:203], v[84:87]
	v_mfma_f32_16x16x32_bf16 v[76:79], v[216:219], v[208:211], v[76:79]
	v_mfma_f32_16x16x32_bf16 v[68:71], v[224:227], v[208:211], v[68:71]
	s_setprio 2
	s_mov_b32 m0, s60
	s_barrier
	ds_read_b128 v[180:183], v144 offset:49152
	ds_read_b128 v[184:187], v144 offset:50176
	ds_read_b128 v[188:191], v144 offset:51200
	ds_read_b128 v[192:195], v144 offset:52224
	ds_read_b128 v[196:199], v144 offset:53248
	ds_read_b128 v[200:203], v144 offset:54272
	ds_read_b128 v[204:207], v144 offset:55296
	ds_read_b128 v[208:211], v144 offset:56320
	global_load_lds_dwordx4 v138, s[56:57]
	s_mov_b32 m0, s61
	s_nop 0
	global_load_lds_dwordx4 v140, s[56:57]
	s_waitcnt vmcnt(10)
	s_barrier
	s_waitcnt lgkmcnt(0)
	s_setprio 0
	v_mfma_f32_16x16x32_bf16 v[64:67], v[146:149], v[180:183], v[64:67]
	v_mfma_f32_16x16x32_bf16 v[56:59], v[154:157], v[180:183], v[56:59]
	v_mfma_f32_16x16x32_bf16 v[48:51], v[146:149], v[188:191], v[48:51]
	v_mfma_f32_16x16x32_bf16 v[40:43], v[154:157], v[188:191], v[40:43]
	v_mfma_f32_16x16x32_bf16 v[32:35], v[146:149], v[196:199], v[32:35]
	v_mfma_f32_16x16x32_bf16 v[24:27], v[154:157], v[196:199], v[24:27]
	v_mfma_f32_16x16x32_bf16 v[16:19], v[146:149], v[204:207], v[16:19]
	v_mfma_f32_16x16x32_bf16 v[8:11], v[154:157], v[204:207], v[8:11]
	v_mfma_f32_16x16x32_bf16 v[64:67], v[150:153], v[184:187], v[64:67]
	v_mfma_f32_16x16x32_bf16 v[56:59], v[176:179], v[184:187], v[56:59]
	v_mfma_f32_16x16x32_bf16 v[48:51], v[150:153], v[192:195], v[48:51]
	v_mfma_f32_16x16x32_bf16 v[40:43], v[176:179], v[192:195], v[40:43]
	v_mfma_f32_16x16x32_bf16 v[32:35], v[150:153], v[200:203], v[32:35]
	v_mfma_f32_16x16x32_bf16 v[24:27], v[176:179], v[200:203], v[24:27]
	s_setprio 3
	s_barrier
; __device__ __forceinline__ unsigned cvt_pk_bf16(float lo, float hi) { f32x2 v = {lo, hi}; bf16x2v b = __builtin_convertvector(v, bf16x2v); return __builtin_bit_cast(unsigned, b); }
; __device__ __forceinline__ float silu_f(float x) { return x * __builtin_amdgcn_rcpf(1.f + __expf(-x)); }
; #define PG8_STAGE(bufoff, gbase, voff) do { _Pragma("unroll") for (int _i = 0; _i < 2; ++_i) \
;         __builtin_amdgcn_global_load_lds((const unsigned*)((const char*)(gbase) + (voff)[_i]), (LAS unsigned*)(lds + (bufoff) + ldsw + _i * 8192), 16, 0, 0); } while (0)
; #define PG8_MMA(ai, bj, At, Bt) do { __builtin_amdgcn_s_setprio(1); _Pragma("unroll") for (int m = 0; m < 4; ++m) _Pragma("unroll") for (int n = 0; n < 2; ++n) _Pragma("unroll") for (int k = 0; k < 2; ++k) \
;         acc[ai][bj][m][n] = __builtin_amdgcn_mfma_f32_16x16x32_bf16(Bt[n][k], At[m][k], acc[ai][bj][m][n], 0, 0, 0); __builtin_amdgcn_s_setprio(0); } while (0)
; #define PG8_WAIT_V(n) asm volatile("s_waitcnt vmcnt(" #n ")" ::: "memory")
;     __device__ __forceinline__ void operator()(const f32x4 (&acc)[2][2][4][2], const Unit& u, int wr, int wc, int fr, int fq) const {
;         const int row0 = u.pm * BM + wr * 64 + fr, col0 = u.pn * 128 + wc * 32 + 8 * fq;
; #pragma unroll
;         for (int ai = 0; ai < 2; ++ai)
; #pragma unroll
;             for (int m = 0; m < 4; ++m) {
;                 bf16_t* rowp = O + img_off(row0 + ai * HALF + m * 16, col0, D_FF / 64);
;                 const f32x4 g0 = acc[ai][0][m][0], g1 = acc[ai][0][m][1], u0 = acc[ai][1][m][0], u1 = acc[ai][1][m][1];
;                 u32x4 w;
;                 w.x = cvt_pk_bf16(silu_f(g0[0]) * u0[0], silu_f(g0[1]) * u0[1]); w.y = cvt_pk_bf16(silu_f(g0[2]) * u0[2], silu_f(g0[3]) * u0[3]);
;                 w.z = cvt_pk_bf16(silu_f(g1[0]) * u1[0], silu_f(g1[1]) * u1[1]); w.w = cvt_pk_bf16(silu_f(g1[2]) * u1[2], silu_f(g1[3]) * u1[3]);
;                 *(u32x4*)rowp = w;
; template <class Epi, class Sched, int LD>
; __device__ __forceinline__ void gemm_phase(LAS unsigned char* lds, const Gemm g, const Sched& S, const Epi& E) {
;     ...
;             PG8_BAR; PG8_WAIT_L(0); PG8_MMA(1, 0, At, B0); PG8_BAR; PG8_SCHED;
;             PG8_STAGE(PG8_SB(1, 1), b3 + hstep, voffB);
;             PG8_WAIT_V(6); PG8_BAR; PG8_MMA(1, 1, At, B1); PG8_BAR;
;         }
;         E(acc, cur, wr, wc, fr, fq);
;         if (!has_next) break;
	v_mfma_f32_16x16x32_bf16 v[16:19], v[150:153], v[208:211], v[16:19]
	v_mfma_f32_16x16x32_bf16 v[8:11], v[176:179], v[208:211], v[8:11]
	s_setprio 2
	ds_read_b128 v[146:149], v228
	ds_read_b128 v[150:153], v228 offset:1024
	ds_read_b128 v[154:157], v228 offset:2048
	ds_read_b128 v[176:179], v228 offset:3072
	s_add_u32 s4, s54, 0xc000
	s_addc_u32 s5, s55, 0
	s_add_i32 s54, s72, s28
	s_mov_b32 m0, s54
	s_nop 0
	global_load_lds_dwordx4 v138, s[4:5]
	s_add_i32 m0, s54, 0x2000
	s_nop 0
	global_load_lds_dwordx4 v140, s[4:5]
	s_waitcnt vmcnt(6)
	s_barrier
	s_setprio 0
	v_mfma_f32_16x16x32_bf16 v[60:63], v[212:215], v[180:183], v[60:63]
	v_mfma_f32_16x16x32_bf16 v[52:55], v[220:223], v[180:183], v[52:55]
	v_mfma_f32_16x16x32_bf16 v[44:47], v[212:215], v[188:191], v[44:47]
	v_mfma_f32_16x16x32_bf16 v[36:39], v[220:223], v[188:191], v[36:39]
	v_mfma_f32_16x16x32_bf16 v[28:31], v[212:215], v[196:199], v[28:31]
	v_mfma_f32_16x16x32_bf16 v[20:23], v[220:223], v[196:199], v[20:23]
	v_mfma_f32_16x16x32_bf16 v[12:15], v[212:215], v[204:207], v[12:15]
	v_mfma_f32_16x16x32_bf16 v[4:7], v[220:223], v[204:207], v[4:7]
	v_mfma_f32_16x16x32_bf16 v[60:63], v[216:219], v[184:187], v[60:63]
	v_mfma_f32_16x16x32_bf16 v[52:55], v[224:227], v[184:187], v[52:55]
	v_mfma_f32_16x16x32_bf16 v[44:47], v[216:219], v[192:195], v[44:47]
	v_mfma_f32_16x16x32_bf16 v[36:39], v[224:227], v[192:195], v[36:39]
	v_mfma_f32_16x16x32_bf16 v[28:31], v[216:219], v[200:203], v[28:31]
	v_mfma_f32_16x16x32_bf16 v[20:23], v[224:227], v[200:203], v[20:23]
	v_mfma_f32_16x16x32_bf16 v[12:15], v[216:219], v[208:211], v[12:15]
	v_mfma_f32_16x16x32_bf16 v[4:7], v[224:227], v[208:211], v[4:7]
	s_setprio 2
	s_add_i32 s70, s70, 2
	s_add_u32 s50, s50, 0x10000
	s_addc_u32 s51, s51, 0
	s_add_u32 s45, s45, 0x10000
	s_addc_u32 s47, s47, 0
	s_add_u32 s4, s50, 0x4000
	s_addc_u32 s5, s51, 0
	s_cmp_eq_u32 s70, 28
	s_cselect_b32 s4, s48, s4
	s_cselect_b32 s5, s49, s5
	s_cselect_b32 s54, s40, s45
	s_cselect_b32 s55, s41, s47
	s_add_u32 s56, s4, 0x8000
	s_addc_u32 s57, s5, 0
	s_add_i32 s71, 0, 0x10000
	s_cmp_gt_u32 s70, 29
	s_cbranch_scc0 .LBB0_899
	s_barrier
	s_setprio 0
	v_mul_f32_e32 v148, 0xbfb8aa3b, v128
	v_mul_f32_e32 v149, 0xbfb8aa3b, v129
	v_exp_f32_e32 v148, v148
	v_exp_f32_e32 v149, v149
	s_lshl_b32 s5, s69, 8
	s_add_i32 s5, s5, s58
	v_add_f32_e32 v148, 1.0, v148
	v_add_f32_e32 v149, 1.0, v149
	v_rcp_f32_e32 v148, v148
	v_rcp_f32_e32 v149, v149
	s_lshl_b32 s4, s68, 7
	s_or_b32 s4, s4, s59
	s_ashr_i32 s45, s5, 8
	v_pk_mul_f32 v[128:129], v[128:129], v[148:149]
	s_ashr_i32 s4, s4, 6
	v_pk_mul_f32 v[124:125], v[128:129], v[124:125]
	s_mulk_i32 s45, 0x58
	v_cvt_pk_bf16_f32 v124, v124, v125
	v_mul_f32_e32 v125, 0xbfb8aa3b, v130
	v_exp_f32_e32 v125, v125
	s_add_i32 s50, s45, s4
	s_ashr_i32 s51, s50, 31
	s_lshl_b64 s[50:51], s[50:51], 15
	v_add_f32_e32 v125, 1.0, v125
	v_rcp_f32_e32 v128, v125
	v_mul_f32_e32 v125, 0xbfb8aa3b, v131
	v_exp_f32_e32 v125, v125
	s_add_u32 s45, s16, s50
	s_addc_u32 s47, s17, s51
	s_lshl_b32 s50, s5, 7
	v_add_f32_e32 v125, 1.0, v125
	v_rcp_f32_e32 v129, v125
	s_and_b32 s50, s50, 0x4000
	s_add_u32 s50, s45, s50
	s_addc_u32 s51, s47, 0
	v_pk_mul_f32 v[128:129], v[130:131], v[128:129]
	s_or_b32 s45, s5, 16
	v_pk_mul_f32 v[126:127], v[128:129], v[126:127]
	s_lshr_b32 s45, s45, 3
	v_cvt_pk_bf16_f32 v125, v126, v127
	v_mul_f32_e32 v126, 0xbfb8aa3b, v120
	v_mul_f32_e32 v127, 0xbfb8aa3b, v121
	v_exp_f32_e32 v126, v126
	v_exp_f32_e32 v127, v127
	v_or_b32_e32 v145, s5, v137
	s_and_b32 s45, s45, 10
	v_add_f32_e32 v126, 1.0, v126
	v_add_f32_e32 v127, 1.0, v127
	v_rcp_f32_e32 v126, v126
	v_rcp_f32_e32 v127, v127
	v_lshlrev_b32_e32 v132, 6, v145
	v_lshlrev_b32_e32 v146, 2, v145
	s_or_b32 s45, s45, s64
	v_pk_mul_f32 v[120:121], v[120:121], v[126:127]
	v_and_or_b32 v132, v132, s15, v142
	v_pk_mul_f32 v[116:117], v[120:121], v[116:117]
	v_and_b32_e32 v146, 32, v146
	v_cvt_pk_bf16_f32 v126, v116, v117
	v_mul_f32_e32 v116, 0xbfb8aa3b, v122
	v_mul_f32_e32 v117, 0xbfb8aa3b, v123
	v_exp_f32_e32 v116, v116
	v_exp_f32_e32 v117, v117
	s_lshl_b32 s45, s45, 10
	v_bitop3_b32 v147, v132, s65, v146 bitop3:0xde
	v_add_f32_e32 v116, 1.0, v116
	v_add_f32_e32 v117, 1.0, v117
	v_rcp_f32_e32 v116, v116
	v_rcp_f32_e32 v117, v117
	s_and_b64 vcc, exec, s[42:43]
	s_mov_b32 s68, s44
	s_mov_b32 s69, s46
	v_pk_mul_f32 v[116:117], v[122:123], v[116:117]
	s_mov_b64 s[54:55], s[40:41]
	v_pk_mul_f32 v[116:117], v[116:117], v[118:119]
	v_bitop3_b32 v118, v132, s45, v146 bitop3:0xde
	v_cvt_pk_bf16_f32 v127, v116, v117
	v_mul_f32_e32 v116, 0xbfb8aa3b, v112
	v_mul_f32_e32 v117, 0xbfb8aa3b, v113
	v_exp_f32_e32 v116, v116
	v_exp_f32_e32 v117, v117
	s_or_b32 s45, s5, 32
	s_or_b32 s5, s5, 48
	v_add_f32_e32 v116, 1.0, v116
	v_add_f32_e32 v117, 1.0, v117
	v_rcp_f32_e32 v116, v116
	v_rcp_f32_e32 v117, v117
	s_lshr_b32 s45, s45, 3
	s_lshr_b32 s5, s5, 3
	s_and_b32 s45, s45, 12
	v_pk_mul_f32 v[112:113], v[112:113], v[116:117]
	s_and_b32 s5, s5, 14
	v_pk_mul_f32 v[108:109], v[112:113], v[108:109]
	s_or_b32 s45, s45, s64
	v_cvt_pk_bf16_f32 v108, v108, v109
	v_mul_f32_e32 v109, 0xbfb8aa3b, v114
	v_exp_f32_e32 v109, v109
	s_or_b32 s5, s5, s64
	s_lshl_b32 s45, s45, 10
	s_lshl_b32 s5, s5, 10
	v_add_f32_e32 v109, 1.0, v109
	v_rcp_f32_e32 v112, v109
	v_mul_f32_e32 v109, 0xbfb8aa3b, v115
	v_exp_f32_e32 v109, v109
	global_store_dwordx4 v147, v[124:127], s[50:51]
	v_add_f32_e32 v109, 1.0, v109
	v_rcp_f32_e32 v113, v109
	s_nop 0
	v_pk_mul_f32 v[112:113], v[114:115], v[112:113]
	s_nop 0
	v_pk_mul_f32 v[110:111], v[112:113], v[110:111]
	s_nop 0
	v_cvt_pk_bf16_f32 v109, v110, v111
	v_mul_f32_e32 v110, 0xbfb8aa3b, v104
	v_mul_f32_e32 v111, 0xbfb8aa3b, v105
; __device__ __forceinline__ unsigned cvt_pk_bf16(float lo, float hi) { f32x2 v = {lo, hi}; bf16x2v b = __builtin_convertvector(v, bf16x2v); return __builtin_bit_cast(unsigned, b); }
; __device__ __forceinline__ float silu_f(float x) { return x * __builtin_amdgcn_rcpf(1.f + __expf(-x)); }
;     __device__ __forceinline__ void operator()(const f32x4 (&acc)[2][2][4][2], const Unit& u, int wr, int wc, int fr, int fq) const {
;     ...
;                 bf16_t* rowp = O + img_off(row0 + ai * HALF + m * 16, col0, D_FF / 64);
;                 const f32x4 g0 = acc[ai][0][m][0], g1 = acc[ai][0][m][1], u0 = acc[ai][1][m][0], u1 = acc[ai][1][m][1];
;                 u32x4 w;
;                 w.x = cvt_pk_bf16(silu_f(g0[0]) * u0[0], silu_f(g0[1]) * u0[1]); w.y = cvt_pk_bf16(silu_f(g0[2]) * u0[2], silu_f(g0[3]) * u0[3]);
;                 w.z = cvt_pk_bf16(silu_f(g1[0]) * u1[0], silu_f(g1[1]) * u1[1]); w.w = cvt_pk_bf16(silu_f(g1[2]) * u1[2], silu_f(g1[3]) * u1[3]);
;                 *(u32x4*)rowp = w;
	v_exp_f32_e32 v110, v110
	v_exp_f32_e32 v111, v111
	v_add_f32_e32 v110, 1.0, v110
	v_add_f32_e32 v111, 1.0, v111
	v_rcp_f32_e32 v110, v110
	v_rcp_f32_e32 v111, v111
	s_nop 0
	v_pk_mul_f32 v[104:105], v[104:105], v[110:111]
	s_nop 0
	v_pk_mul_f32 v[100:101], v[104:105], v[100:101]
	s_nop 0
	v_cvt_pk_bf16_f32 v110, v100, v101
	v_mul_f32_e32 v100, 0xbfb8aa3b, v106
	v_mul_f32_e32 v101, 0xbfb8aa3b, v107
	v_exp_f32_e32 v100, v100
	v_exp_f32_e32 v101, v101
	v_add_f32_e32 v100, 1.0, v100
	v_add_f32_e32 v101, 1.0, v101
	v_rcp_f32_e32 v100, v100
	v_rcp_f32_e32 v101, v101
	s_nop 0
	v_pk_mul_f32 v[100:101], v[106:107], v[100:101]
	s_nop 0
	v_pk_mul_f32 v[100:101], v[100:101], v[102:103]
	v_bitop3_b32 v102, v132, s45, v146 bitop3:0xde
	v_cvt_pk_bf16_f32 v111, v100, v101
	v_mul_f32_e32 v100, 0xbfb8aa3b, v96
	v_mul_f32_e32 v101, 0xbfb8aa3b, v97
	v_exp_f32_e32 v100, v100
	v_exp_f32_e32 v101, v101
	global_store_dwordx4 v118, v[108:111], s[50:51]
	v_add_f32_e32 v100, 1.0, v100
	v_add_f32_e32 v101, 1.0, v101
	v_rcp_f32_e32 v100, v100
	v_rcp_f32_e32 v101, v101
	s_nop 0
	v_pk_mul_f32 v[96:97], v[96:97], v[100:101]
	s_nop 0
	v_pk_mul_f32 v[92:93], v[96:97], v[92:93]
	s_nop 0
	v_cvt_pk_bf16_f32 v92, v92, v93
	v_mul_f32_e32 v93, 0xbfb8aa3b, v98
	v_exp_f32_e32 v93, v93
	s_nop 0
	v_add_f32_e32 v93, 1.0, v93
	v_rcp_f32_e32 v96, v93
	v_mul_f32_e32 v93, 0xbfb8aa3b, v99
	v_exp_f32_e32 v93, v93
	s_nop 0
	v_add_f32_e32 v93, 1.0, v93
	v_rcp_f32_e32 v97, v93
	s_nop 0
	v_pk_mul_f32 v[96:97], v[98:99], v[96:97]
	s_nop 0
	v_pk_mul_f32 v[94:95], v[96:97], v[94:95]
	s_nop 0
	v_cvt_pk_bf16_f32 v93, v94, v95
	v_mul_f32_e32 v94, 0xbfb8aa3b, v88
	v_mul_f32_e32 v95, 0xbfb8aa3b, v89
	v_exp_f32_e32 v94, v94
	v_exp_f32_e32 v95, v95
	v_add_f32_e32 v94, 1.0, v94
	v_add_f32_e32 v95, 1.0, v95
	v_rcp_f32_e32 v94, v94
	v_rcp_f32_e32 v95, v95
	s_nop 0
	v_pk_mul_f32 v[88:89], v[88:89], v[94:95]
	s_nop 0
	v_pk_mul_f32 v[84:85], v[88:89], v[84:85]
	s_nop 0
	v_cvt_pk_bf16_f32 v94, v84, v85
	v_mul_f32_e32 v84, 0xbfb8aa3b, v90
	v_mul_f32_e32 v85, 0xbfb8aa3b, v91
	v_exp_f32_e32 v84, v84
	v_exp_f32_e32 v85, v85
	v_add_f32_e32 v84, 1.0, v84
	v_add_f32_e32 v85, 1.0, v85
	v_rcp_f32_e32 v84, v84
	v_rcp_f32_e32 v85, v85
	s_nop 0
	v_pk_mul_f32 v[84:85], v[90:91], v[84:85]
	s_nop 0
	v_pk_mul_f32 v[84:85], v[84:85], v[86:87]
	v_bitop3_b32 v86, v132, s5, v146 bitop3:0xde
	v_cvt_pk_bf16_f32 v95, v84, v85
	v_mul_f32_e32 v84, 0xbfb8aa3b, v80
	v_mul_f32_e32 v85, 0xbfb8aa3b, v81
	v_exp_f32_e32 v84, v84
	v_exp_f32_e32 v85, v85
	global_store_dwordx4 v102, v[92:95], s[50:51]
	v_add_f32_e32 v84, 1.0, v84
	v_add_f32_e32 v85, 1.0, v85
	v_rcp_f32_e32 v84, v84
	v_rcp_f32_e32 v85, v85
	s_nop 0
	v_pk_mul_f32 v[80:81], v[80:81], v[84:85]
	s_nop 0
	v_pk_mul_f32 v[76:77], v[80:81], v[76:77]
	s_nop 0
	v_cvt_pk_bf16_f32 v76, v76, v77
	v_mul_f32_e32 v77, 0xbfb8aa3b, v82
	v_exp_f32_e32 v77, v77
	s_nop 0
	v_add_f32_e32 v77, 1.0, v77
	v_rcp_f32_e32 v80, v77
	v_mul_f32_e32 v77, 0xbfb8aa3b, v83
	v_exp_f32_e32 v77, v77
	s_nop 0
	v_add_f32_e32 v77, 1.0, v77
	v_rcp_f32_e32 v81, v77
	s_nop 0
	v_pk_mul_f32 v[80:81], v[82:83], v[80:81]
	s_nop 0
	v_pk_mul_f32 v[78:79], v[80:81], v[78:79]
	s_nop 0
	v_cvt_pk_bf16_f32 v77, v78, v79
	v_mul_f32_e32 v78, 0xbfb8aa3b, v72
	v_mul_f32_e32 v79, 0xbfb8aa3b, v73
	v_exp_f32_e32 v78, v78
	v_exp_f32_e32 v79, v79
	v_add_f32_e32 v78, 1.0, v78
	v_add_f32_e32 v79, 1.0, v79
	v_rcp_f32_e32 v78, v78
	v_rcp_f32_e32 v79, v79
	s_nop 0
	v_pk_mul_f32 v[72:73], v[72:73], v[78:79]
	s_nop 0
	v_pk_mul_f32 v[68:69], v[72:73], v[68:69]
	v_mul_f32_e32 v73, 0xbfb8aa3b, v65
	v_cvt_pk_bf16_f32 v78, v68, v69
	v_mul_f32_e32 v68, 0xbfb8aa3b, v74
	v_mul_f32_e32 v69, 0xbfb8aa3b, v75
	v_exp_f32_e32 v68, v68
	v_exp_f32_e32 v69, v69
	v_exp_f32_e32 v73, v73
	v_add_f32_e32 v68, 1.0, v68
	v_add_f32_e32 v69, 1.0, v69
	v_rcp_f32_e32 v68, v68
	v_rcp_f32_e32 v69, v69
	v_add_f32_e32 v73, 1.0, v73
	v_rcp_f32_e32 v73, v73
	v_pk_mul_f32 v[68:69], v[74:75], v[68:69]
	s_nop 0
	v_pk_mul_f32 v[68:69], v[68:69], v[70:71]
	v_add_u32_e32 v70, 0x80, v145
	v_lshlrev_b32_e32 v71, 6, v70
	v_lshlrev_b32_e32 v72, 2, v70
	v_and_or_b32 v71, v71, s15, v142
	v_and_b32_e32 v72, 32, v72
	v_bitop3_b32 v132, v71, s65, v72 bitop3:0xde
	v_mul_f32_e32 v72, 0xbfb8aa3b, v64
	v_exp_f32_e32 v72, v72
	v_cvt_pk_bf16_f32 v79, v68, v69
	v_lshrrev_b32_e32 v68, 8, v70
	v_mov_b32_e32 v69, s4
	v_add_f32_e32 v72, 1.0, v72
	v_rcp_f32_e32 v72, v72
	s_movk_i32 s4, 0x58
	v_mad_i32_i24 v68, v68, s4, v69
	v_ashrrev_i32_e32 v69, 31, v68
	v_pk_mul_f32 v[64:65], v[64:65], v[72:73]
	v_lshlrev_b64 v[68:69], 15, v[68:69]
	v_pk_mul_f32 v[60:61], v[64:65], v[60:61]
	v_lshlrev_b32_e32 v70, 7, v70
	v_cvt_pk_bf16_f32 v60, v60, v61
	v_mul_f32_e32 v61, 0xbfb8aa3b, v66
	v_exp_f32_e32 v61, v61
	v_lshl_add_u64 v[68:69], s[16:17], 0, v[68:69]
	v_and_b32_e32 v70, 0x4000, v70
	v_mov_b32_e32 v71, v133
	v_add_f32_e32 v61, 1.0, v61
	v_rcp_f32_e32 v64, v61
	v_mul_f32_e32 v61, 0xbfb8aa3b, v67
	v_exp_f32_e32 v61, v61
	v_lshl_add_u64 v[70:71], v[68:69], 0, v[70:71]
	v_lshl_add_u64 v[70:71], v[70:71], 0, v[132:133]
	s_mov_b64 s[4:5], s[48:49]
	v_add_f32_e32 v61, 1.0, v61
	v_rcp_f32_e32 v65, v61
	global_store_dwordx4 v86, v[76:79], s[50:51]
	v_pk_mul_f32 v[64:65], v[66:67], v[64:65]
	s_nop 0
	v_pk_mul_f32 v[62:63], v[64:65], v[62:63]
	s_nop 0
	v_cvt_pk_bf16_f32 v61, v62, v63
	v_mul_f32_e32 v62, 0xbfb8aa3b, v56
	v_mul_f32_e32 v63, 0xbfb8aa3b, v57
	v_exp_f32_e32 v62, v62
	v_exp_f32_e32 v63, v63
	v_add_f32_e32 v62, 1.0, v62
	v_add_f32_e32 v63, 1.0, v63
	v_rcp_f32_e32 v62, v62
	v_rcp_f32_e32 v63, v63
	s_nop 0
	v_pk_mul_f32 v[56:57], v[56:57], v[62:63]
	s_nop 0
	v_pk_mul_f32 v[52:53], v[56:57], v[52:53]
	s_nop 0
; __device__ __forceinline__ unsigned cvt_pk_bf16(float lo, float hi) { f32x2 v = {lo, hi}; bf16x2v b = __builtin_convertvector(v, bf16x2v); return __builtin_bit_cast(unsigned, b); }
; __device__ __forceinline__ float silu_f(float x) { return x * __builtin_amdgcn_rcpf(1.f + __expf(-x)); }
; #define PG8_WAIT_V(n) asm volatile("s_waitcnt vmcnt(" #n ")" ::: "memory")
; #define PG8_BAR __builtin_amdgcn_s_barrier()
;     __device__ __forceinline__ void operator()(const f32x4 (&acc)[2][2][4][2], const Unit& u, int wr, int wc, int fr, int fq) const {
;     ...
;                 bf16_t* rowp = O + img_off(row0 + ai * HALF + m * 16, col0, D_FF / 64);
;                 const f32x4 g0 = acc[ai][0][m][0], g1 = acc[ai][0][m][1], u0 = acc[ai][1][m][0], u1 = acc[ai][1][m][1];
;                 u32x4 w;
;                 w.x = cvt_pk_bf16(silu_f(g0[0]) * u0[0], silu_f(g0[1]) * u0[1]); w.y = cvt_pk_bf16(silu_f(g0[2]) * u0[2], silu_f(g0[3]) * u0[3]);
;                 w.z = cvt_pk_bf16(silu_f(g1[0]) * u1[0], silu_f(g1[1]) * u1[1]); w.w = cvt_pk_bf16(silu_f(g1[2]) * u1[2], silu_f(g1[3]) * u1[3]);
;                 *(u32x4*)rowp = w;
; template <class Epi, class Sched, int LD>
; __device__ __forceinline__ void gemm_phase(LAS unsigned char* lds, const Gemm g, const Sched& S, const Epi& E) {
;     ...
;         E(acc, cur, wr, wc, fr, fq);
;         if (!has_next) break;
; #pragma unroll
;         for (int a = 0; a < 2; ++a)
; #pragma unroll
;             for (int b = 0; b < 2; ++b)
; #pragma unroll
;                 for (int m = 0; m < 4; ++m)
; #pragma unroll
;                     for (int n = 0; n < 2; ++n) acc[a][b][m][n] = (f32x4){0.f, 0.f, 0.f, 0.f};
;         cur = nxt; cA = nA; cB = nB; ++ui;
;     }
;     PG8_WAIT_V(0);
;     if (wr == 0) PG8_BAR;
	v_cvt_pk_bf16_f32 v62, v52, v53
	v_mul_f32_e32 v52, 0xbfb8aa3b, v58
	v_mul_f32_e32 v53, 0xbfb8aa3b, v59
	v_exp_f32_e32 v52, v52
	v_exp_f32_e32 v53, v53
	v_add_f32_e32 v52, 1.0, v52
	v_add_f32_e32 v53, 1.0, v53
	v_rcp_f32_e32 v52, v52
	v_rcp_f32_e32 v53, v53
	s_nop 0
	v_pk_mul_f32 v[52:53], v[58:59], v[52:53]
	s_nop 0
	v_pk_mul_f32 v[52:53], v[52:53], v[54:55]
	s_nop 0
	v_cvt_pk_bf16_f32 v63, v52, v53
	v_add_u32_e32 v52, 0x90, v145
	v_lshrrev_b32_e32 v54, 3, v52
	v_lshlrev_b32_e32 v53, 6, v52
	v_and_or_b32 v54, v54, 10, s64
	v_lshlrev_b32_e32 v55, 2, v52
	v_and_or_b32 v53, v53, s15, v142
	v_lshlrev_b32_e32 v54, 10, v54
	v_and_b32_e32 v55, 32, v55
	v_bitop3_b32 v132, v53, v54, v55 bitop3:0xde
	v_mul_f32_e32 v54, 0xbfb8aa3b, v48
	v_mul_f32_e32 v55, 0xbfb8aa3b, v49
	v_exp_f32_e32 v54, v54
	v_exp_f32_e32 v55, v55
	v_lshlrev_b32_e32 v52, 7, v52
	v_and_b32_e32 v52, 0x4000, v52
	v_add_f32_e32 v54, 1.0, v54
	v_add_f32_e32 v55, 1.0, v55
	v_rcp_f32_e32 v54, v54
	v_rcp_f32_e32 v55, v55
	v_mov_b32_e32 v53, v133
	v_lshl_add_u64 v[52:53], v[68:69], 0, v[52:53]
	v_lshl_add_u64 v[52:53], v[52:53], 0, v[132:133]
	v_pk_mul_f32 v[48:49], v[48:49], v[54:55]
	global_store_dwordx4 v[70:71], v[60:63], off
	v_pk_mul_f32 v[44:45], v[48:49], v[44:45]
	s_nop 0
	v_cvt_pk_bf16_f32 v44, v44, v45
	v_mul_f32_e32 v45, 0xbfb8aa3b, v50
	v_exp_f32_e32 v45, v45
	s_nop 0
	v_add_f32_e32 v45, 1.0, v45
	v_rcp_f32_e32 v48, v45
	v_mul_f32_e32 v45, 0xbfb8aa3b, v51
	v_exp_f32_e32 v45, v45
	s_nop 0
	v_add_f32_e32 v45, 1.0, v45
	v_rcp_f32_e32 v49, v45
	s_nop 0
	v_pk_mul_f32 v[48:49], v[50:51], v[48:49]
	s_nop 0
	v_pk_mul_f32 v[46:47], v[48:49], v[46:47]
	s_nop 0
	v_cvt_pk_bf16_f32 v45, v46, v47
	v_mul_f32_e32 v46, 0xbfb8aa3b, v40
	v_mul_f32_e32 v47, 0xbfb8aa3b, v41
	v_exp_f32_e32 v46, v46
	v_exp_f32_e32 v47, v47
	v_add_f32_e32 v46, 1.0, v46
	v_add_f32_e32 v47, 1.0, v47
	v_rcp_f32_e32 v46, v46
	v_rcp_f32_e32 v47, v47
	s_nop 0
	v_pk_mul_f32 v[40:41], v[40:41], v[46:47]
	s_nop 0
	v_pk_mul_f32 v[36:37], v[40:41], v[36:37]
	s_nop 0
	v_cvt_pk_bf16_f32 v46, v36, v37
	v_mul_f32_e32 v36, 0xbfb8aa3b, v42
	v_mul_f32_e32 v37, 0xbfb8aa3b, v43
	v_exp_f32_e32 v36, v36
	v_exp_f32_e32 v37, v37
	v_add_f32_e32 v36, 1.0, v36
	v_add_f32_e32 v37, 1.0, v37
	v_rcp_f32_e32 v36, v36
	v_rcp_f32_e32 v37, v37
	s_nop 0
	v_pk_mul_f32 v[36:37], v[42:43], v[36:37]
	s_nop 0
	v_pk_mul_f32 v[36:37], v[36:37], v[38:39]
	s_nop 0
	v_cvt_pk_bf16_f32 v47, v36, v37
	v_add_u32_e32 v36, 0xa0, v145
	v_lshrrev_b32_e32 v38, 3, v36
	v_lshlrev_b32_e32 v37, 6, v36
	v_and_or_b32 v38, v38, 12, s64
	v_lshlrev_b32_e32 v39, 2, v36
	v_and_or_b32 v37, v37, s15, v142
	v_lshlrev_b32_e32 v38, 10, v38
	v_and_b32_e32 v39, 32, v39
	v_bitop3_b32 v132, v37, v38, v39 bitop3:0xde
	v_mul_f32_e32 v38, 0xbfb8aa3b, v32
	v_mul_f32_e32 v39, 0xbfb8aa3b, v33
	v_exp_f32_e32 v38, v38
	v_exp_f32_e32 v39, v39
	v_lshlrev_b32_e32 v36, 7, v36
	v_and_b32_e32 v36, 0x4000, v36
	v_add_f32_e32 v38, 1.0, v38
	v_add_f32_e32 v39, 1.0, v39
	v_rcp_f32_e32 v38, v38
	v_rcp_f32_e32 v39, v39
	v_mov_b32_e32 v37, v133
	v_lshl_add_u64 v[36:37], v[68:69], 0, v[36:37]
	v_lshl_add_u64 v[36:37], v[36:37], 0, v[132:133]
	v_pk_mul_f32 v[32:33], v[32:33], v[38:39]
	global_store_dwordx4 v[52:53], v[44:47], off
	v_pk_mul_f32 v[28:29], v[32:33], v[28:29]
	s_nop 0
	v_cvt_pk_bf16_f32 v28, v28, v29
	v_mul_f32_e32 v29, 0xbfb8aa3b, v34
	v_exp_f32_e32 v29, v29
	s_nop 0
	v_add_f32_e32 v29, 1.0, v29
	v_rcp_f32_e32 v32, v29
	v_mul_f32_e32 v29, 0xbfb8aa3b, v35
	v_exp_f32_e32 v29, v29
	s_nop 0
	v_add_f32_e32 v29, 1.0, v29
	v_rcp_f32_e32 v33, v29
	s_nop 0
	v_pk_mul_f32 v[32:33], v[34:35], v[32:33]
	s_nop 0
	v_pk_mul_f32 v[30:31], v[32:33], v[30:31]
	s_nop 0
	v_cvt_pk_bf16_f32 v29, v30, v31
	v_mul_f32_e32 v30, 0xbfb8aa3b, v24
	v_mul_f32_e32 v31, 0xbfb8aa3b, v25
	v_exp_f32_e32 v30, v30
	v_exp_f32_e32 v31, v31
	v_add_f32_e32 v30, 1.0, v30
	v_add_f32_e32 v31, 1.0, v31
	v_rcp_f32_e32 v30, v30
	v_rcp_f32_e32 v31, v31
	s_nop 0
	v_pk_mul_f32 v[24:25], v[24:25], v[30:31]
	s_nop 0
	v_pk_mul_f32 v[20:21], v[24:25], v[20:21]
	s_nop 0
	v_cvt_pk_bf16_f32 v30, v20, v21
	v_mul_f32_e32 v20, 0xbfb8aa3b, v26
	v_mul_f32_e32 v21, 0xbfb8aa3b, v27
	v_exp_f32_e32 v20, v20
	v_exp_f32_e32 v21, v21
	v_add_f32_e32 v20, 1.0, v20
	v_add_f32_e32 v21, 1.0, v21
	v_rcp_f32_e32 v20, v20
	v_rcp_f32_e32 v21, v21
	s_nop 0
	v_pk_mul_f32 v[20:21], v[26:27], v[20:21]
	s_nop 0
	v_pk_mul_f32 v[20:21], v[20:21], v[22:23]
	s_nop 0
	v_cvt_pk_bf16_f32 v31, v20, v21
	v_add_u32_e32 v20, 0xb0, v145
	v_lshrrev_b32_e32 v22, 3, v20
	v_lshlrev_b32_e32 v21, 6, v20
	v_and_or_b32 v22, v22, 14, s64
	v_lshlrev_b32_e32 v23, 2, v20
	v_and_or_b32 v21, v21, s15, v142
	v_lshlrev_b32_e32 v22, 10, v22
	v_and_b32_e32 v23, 32, v23
	v_bitop3_b32 v132, v21, v22, v23 bitop3:0xde
	v_mul_f32_e32 v22, 0xbfb8aa3b, v16
	v_mul_f32_e32 v23, 0xbfb8aa3b, v17
	v_exp_f32_e32 v22, v22
	v_exp_f32_e32 v23, v23
	v_lshlrev_b32_e32 v20, 7, v20
	v_and_b32_e32 v20, 0x4000, v20
	v_add_f32_e32 v22, 1.0, v22
	v_add_f32_e32 v23, 1.0, v23
	v_rcp_f32_e32 v22, v22
	v_rcp_f32_e32 v23, v23
	v_mov_b32_e32 v21, v133
	v_lshl_add_u64 v[20:21], v[68:69], 0, v[20:21]
	v_lshl_add_u64 v[20:21], v[20:21], 0, v[132:133]
	v_pk_mul_f32 v[16:17], v[16:17], v[22:23]
	global_store_dwordx4 v[36:37], v[28:31], off
	v_pk_mul_f32 v[12:13], v[16:17], v[12:13]
	s_nop 0
	v_cvt_pk_bf16_f32 v12, v12, v13
	v_mul_f32_e32 v13, 0xbfb8aa3b, v18
	v_exp_f32_e32 v13, v13
	s_nop 0
	v_add_f32_e32 v13, 1.0, v13
	v_rcp_f32_e32 v16, v13
	v_mul_f32_e32 v13, 0xbfb8aa3b, v19
	v_exp_f32_e32 v13, v13
	s_nop 0
	v_add_f32_e32 v13, 1.0, v13
	v_rcp_f32_e32 v17, v13
	s_nop 0
	v_pk_mul_f32 v[16:17], v[18:19], v[16:17]
	s_nop 0
	v_pk_mul_f32 v[14:15], v[16:17], v[14:15]
	s_nop 0
	v_cvt_pk_bf16_f32 v13, v14, v15
	v_mul_f32_e32 v14, 0xbfb8aa3b, v8
	v_mul_f32_e32 v15, 0xbfb8aa3b, v9
	v_exp_f32_e32 v14, v14
	v_exp_f32_e32 v15, v15
	v_add_f32_e32 v14, 1.0, v14
	v_add_f32_e32 v15, 1.0, v15
	v_rcp_f32_e32 v14, v14
	v_rcp_f32_e32 v15, v15
	s_nop 0
	v_pk_mul_f32 v[8:9], v[8:9], v[14:15]
	s_nop 0
	v_pk_mul_f32 v[4:5], v[8:9], v[4:5]
	s_nop 0
	v_cvt_pk_bf16_f32 v14, v4, v5
	v_mul_f32_e32 v4, 0xbfb8aa3b, v10
	v_mul_f32_e32 v5, 0xbfb8aa3b, v11
	v_exp_f32_e32 v4, v4
	v_exp_f32_e32 v5, v5
	v_add_f32_e32 v4, 1.0, v4
	v_add_f32_e32 v5, 1.0, v5
	v_rcp_f32_e32 v4, v4
	v_rcp_f32_e32 v5, v5
	s_nop 0
	v_pk_mul_f32 v[4:5], v[10:11], v[4:5]
	s_nop 0
	v_pk_mul_f32 v[4:5], v[4:5], v[6:7]
	s_nop 0
	v_cvt_pk_bf16_f32 v15, v4, v5
	global_store_dwordx4 v[20:21], v[12:15], off
	s_cbranch_vccz .LBB0_892
	s_waitcnt vmcnt(0)
	s_cmpk_gt_u32 s2, 0xff
	s_cbranch_scc1 .LBB0_903
	s_barrier
